# latency de-serialisation of three staging loops: prep_mla row-rms loads, ada_tile silu staging loads and prep_dn conv-weight loads are each issued as one batch with counted waits (arithmetic order unc
# speedup vs baseline: 1.0138x; 1.0078x over previous
; DI float siluf(float x) { return x / (1.f + __expf(-x)); }
; DI void ada_tile(const Params& p, int layer, int cg64, char* lds) {
;     ...
;   for (int e = tid; e < 17 * 1024; e += 256) {
;     int bi = e >> 10, k = e & 1023;
;     float v = bi < 16 ? p.c[bi * 1024 + k] : p.c_ctx[k];
;     sc[e] = siluf(v);
;   }
.LBB0_34:
	s_mov_b32 s100, 0x1000
	s_mov_b32 s101, 0
	v_mov_b32_e32 v4, v0
	v_mov_b32_e32 v5, v1
	global_load_dword v12, v[4:5], off
	global_load_dword v13, v[4:5], off offset:1024
	global_load_dword v14, v[4:5], off offset:2048
	global_load_dword v15, v[4:5], off offset:3072
	v_lshl_add_u64 v[4:5], v[4:5], 0, s[100:101]
	global_load_dword v16, v[4:5], off
	global_load_dword v17, v[4:5], off offset:1024
	global_load_dword v18, v[4:5], off offset:2048
	global_load_dword v19, v[4:5], off offset:3072
	v_lshl_add_u64 v[4:5], v[4:5], 0, s[100:101]
	global_load_dword v20, v[4:5], off
	global_load_dword v21, v[4:5], off offset:1024
	global_load_dword v22, v[4:5], off offset:2048
	global_load_dword v23, v[4:5], off offset:3072
	v_lshl_add_u64 v[4:5], v[4:5], 0, s[100:101]
	global_load_dword v24, v[4:5], off
	global_load_dword v25, v[4:5], off offset:1024
	global_load_dword v26, v[4:5], off offset:2048
	global_load_dword v27, v[4:5], off offset:3072
	v_lshl_add_u64 v[4:5], v[4:5], 0, s[100:101]
	global_load_dword v28, v[4:5], off
	global_load_dword v29, v[4:5], off offset:1024
	global_load_dword v30, v[4:5], off offset:2048
	global_load_dword v31, v[4:5], off offset:3072
	v_lshl_add_u64 v[4:5], v[4:5], 0, s[100:101]
	global_load_dword v32, v[4:5], off
	global_load_dword v33, v[4:5], off offset:1024
	global_load_dword v34, v[4:5], off offset:2048
	global_load_dword v35, v[4:5], off offset:3072
	v_lshl_add_u64 v[4:5], v[4:5], 0, s[100:101]
	global_load_dword v36, v[4:5], off
	global_load_dword v37, v[4:5], off offset:1024
	global_load_dword v38, v[4:5], off offset:2048
	global_load_dword v39, v[4:5], off offset:3072
	v_lshl_add_u64 v[4:5], v[4:5], 0, s[100:101]
	global_load_dword v40, v[4:5], off
	global_load_dword v41, v[4:5], off offset:1024
	global_load_dword v42, v[4:5], off offset:2048
	global_load_dword v43, v[4:5], off offset:3072
	v_lshl_add_u64 v[4:5], v[4:5], 0, s[100:101]
	global_load_dword v44, v[4:5], off
	global_load_dword v45, v[4:5], off offset:1024
	global_load_dword v46, v[4:5], off offset:2048
	global_load_dword v47, v[4:5], off offset:3072
	v_lshl_add_u64 v[4:5], v[4:5], 0, s[100:101]
	global_load_dword v48, v[4:5], off
	global_load_dword v49, v[4:5], off offset:1024
	global_load_dword v50, v[4:5], off offset:2048
	global_load_dword v51, v[4:5], off offset:3072
	v_lshl_add_u64 v[4:5], v[4:5], 0, s[100:101]
	global_load_dword v52, v[4:5], off
	global_load_dword v53, v[4:5], off offset:1024
	global_load_dword v54, v[4:5], off offset:2048
	global_load_dword v55, v[4:5], off offset:3072
	v_lshl_add_u64 v[4:5], v[4:5], 0, s[100:101]
	global_load_dword v56, v[4:5], off
	global_load_dword v57, v[4:5], off offset:1024
	global_load_dword v58, v[4:5], off offset:2048
	global_load_dword v59, v[4:5], off offset:3072
	v_lshl_add_u64 v[4:5], v[4:5], 0, s[100:101]
	global_load_dword v60, v[4:5], off
	global_load_dword v61, v[4:5], off offset:1024
	global_load_dword v62, v[4:5], off offset:2048
	global_load_dword v63, v[4:5], off offset:3072
	v_lshl_add_u64 v[4:5], v[4:5], 0, s[100:101]
	global_load_dword v64, v[4:5], off
	global_load_dword v65, v[4:5], off offset:1024
	global_load_dword v66, v[4:5], off offset:2048
	global_load_dword v67, v[4:5], off offset:3072
	v_lshl_add_u64 v[4:5], v[4:5], 0, s[100:101]
	global_load_dword v68, v[4:5], off
	global_load_dword v69, v[4:5], off offset:1024
	global_load_dword v70, v[4:5], off offset:2048
	global_load_dword v71, v[4:5], off offset:3072
	v_lshl_add_u64 v[4:5], v[4:5], 0, s[100:101]
	global_load_dword v98, v[4:5], off
	global_load_dword v99, v[4:5], off offset:1024
	global_load_dword v100, v[4:5], off offset:2048
	global_load_dword v101, v[4:5], off offset:3072
	v_and_b32_e32 v6, 0x3ff, v3
	v_lshlrev_b32_e32 v74, 2, v6
	v_lshl_add_u64 v[6:7], s[54:55], 0, v[74:75]
	global_load_dword v102, v[6:7], off
	global_load_dword v103, v[6:7], off offset:1024
	global_load_dword v104, v[6:7], off offset:2048
	global_load_dword v105, v[6:7], off offset:3072
	v_add_u32_e32 v11, 0x10000, v2
	s_waitcnt vmcnt(63)
	v_mul_f32_e32 v5, 0xbfb8aa3b, v12
	v_exp_f32_e32 v5, v5
	s_nop 0
	v_add_f32_e32 v5, 1.0, v5
	v_div_scale_f32 v6, s[14:15], v5, v5, v12
	v_rcp_f32_e32 v7, v6
	v_div_scale_f32 v8, vcc, v12, v5, v12
	v_fma_f32 v9, -v6, v7, 1.0
	v_fmac_f32_e32 v7, v9, v7
	v_mul_f32_e32 v9, v8, v7
	v_fma_f32 v10, -v6, v9, v8
	v_fmac_f32_e32 v9, v10, v7
	v_fma_f32 v6, -v6, v9, v8
	v_div_fmas_f32 v6, v6, v7, v9
	v_div_fixup_f32 v12, v6, v5, v12
	ds_write_b32 v2, v12
	s_waitcnt vmcnt(63)
	v_mul_f32_e32 v5, 0xbfb8aa3b, v13
	v_exp_f32_e32 v5, v5
	s_nop 0
	v_add_f32_e32 v5, 1.0, v5
	v_div_scale_f32 v6, s[14:15], v5, v5, v13
	v_rcp_f32_e32 v7, v6
	v_div_scale_f32 v8, vcc, v13, v5, v13
	v_fma_f32 v9, -v6, v7, 1.0
	v_fmac_f32_e32 v7, v9, v7
	v_mul_f32_e32 v9, v8, v7
	v_fma_f32 v10, -v6, v9, v8
	v_fmac_f32_e32 v9, v10, v7
	v_fma_f32 v6, -v6, v9, v8
	v_div_fmas_f32 v6, v6, v7, v9
	v_div_fixup_f32 v13, v6, v5, v13
	ds_write_b32 v2, v13 offset:1024
	s_waitcnt vmcnt(63)
	v_mul_f32_e32 v5, 0xbfb8aa3b, v14
	v_exp_f32_e32 v5, v5
	s_nop 0
	v_add_f32_e32 v5, 1.0, v5
	v_div_scale_f32 v6, s[14:15], v5, v5, v14
	v_rcp_f32_e32 v7, v6
	v_div_scale_f32 v8, vcc, v14, v5, v14
	v_fma_f32 v9, -v6, v7, 1.0
	v_fmac_f32_e32 v7, v9, v7
	v_mul_f32_e32 v9, v8, v7
	v_fma_f32 v10, -v6, v9, v8
	v_fmac_f32_e32 v9, v10, v7
	v_fma_f32 v6, -v6, v9, v8
	v_div_fmas_f32 v6, v6, v7, v9
	v_div_fixup_f32 v14, v6, v5, v14
	ds_write_b32 v2, v14 offset:2048
	s_waitcnt vmcnt(63)
; DI float siluf(float x) { return x / (1.f + __expf(-x)); }
; DI void ada_tile(const Params& p, int layer, int cg64, char* lds) {
;     ...
;   for (int e = tid; e < 17 * 1024; e += 256) {
;     int bi = e >> 10, k = e & 1023;
;     float v = bi < 16 ? p.c[bi * 1024 + k] : p.c_ctx[k];
;     sc[e] = siluf(v);
;   }
	v_mul_f32_e32 v5, 0xbfb8aa3b, v15
	v_exp_f32_e32 v5, v5
	s_nop 0
	v_add_f32_e32 v5, 1.0, v5
	v_div_scale_f32 v6, s[14:15], v5, v5, v15
	v_rcp_f32_e32 v7, v6
	v_div_scale_f32 v8, vcc, v15, v5, v15
	v_fma_f32 v9, -v6, v7, 1.0
	v_fmac_f32_e32 v7, v9, v7
	v_mul_f32_e32 v9, v8, v7
	v_fma_f32 v10, -v6, v9, v8
	v_fmac_f32_e32 v9, v10, v7
	v_fma_f32 v6, -v6, v9, v8
	v_div_fmas_f32 v6, v6, v7, v9
	v_div_fixup_f32 v15, v6, v5, v15
	ds_write_b32 v2, v15 offset:3072
	s_waitcnt vmcnt(63)
	v_mul_f32_e32 v5, 0xbfb8aa3b, v16
	v_exp_f32_e32 v5, v5
	s_nop 0
	v_add_f32_e32 v5, 1.0, v5
	v_div_scale_f32 v6, s[14:15], v5, v5, v16
	v_rcp_f32_e32 v7, v6
	v_div_scale_f32 v8, vcc, v16, v5, v16
	v_fma_f32 v9, -v6, v7, 1.0
	v_fmac_f32_e32 v7, v9, v7
	v_mul_f32_e32 v9, v8, v7
	v_fma_f32 v10, -v6, v9, v8
	v_fmac_f32_e32 v9, v10, v7
	v_fma_f32 v6, -v6, v9, v8
	v_div_fmas_f32 v6, v6, v7, v9
	v_div_fixup_f32 v16, v6, v5, v16
	ds_write_b32 v2, v16 offset:4096
	s_waitcnt vmcnt(62)
	v_mul_f32_e32 v5, 0xbfb8aa3b, v17
	v_exp_f32_e32 v5, v5
	s_nop 0
	v_add_f32_e32 v5, 1.0, v5
	v_div_scale_f32 v6, s[14:15], v5, v5, v17
	v_rcp_f32_e32 v7, v6
	v_div_scale_f32 v8, vcc, v17, v5, v17
	v_fma_f32 v9, -v6, v7, 1.0
	v_fmac_f32_e32 v7, v9, v7
	v_mul_f32_e32 v9, v8, v7
	v_fma_f32 v10, -v6, v9, v8
	v_fmac_f32_e32 v9, v10, v7
	v_fma_f32 v6, -v6, v9, v8
	v_div_fmas_f32 v6, v6, v7, v9
	v_div_fixup_f32 v17, v6, v5, v17
	ds_write_b32 v2, v17 offset:5120
	s_waitcnt vmcnt(61)
	v_mul_f32_e32 v5, 0xbfb8aa3b, v18
	v_exp_f32_e32 v5, v5
	s_nop 0
	v_add_f32_e32 v5, 1.0, v5
	v_div_scale_f32 v6, s[14:15], v5, v5, v18
	v_rcp_f32_e32 v7, v6
	v_div_scale_f32 v8, vcc, v18, v5, v18
	v_fma_f32 v9, -v6, v7, 1.0
	v_fmac_f32_e32 v7, v9, v7
	v_mul_f32_e32 v9, v8, v7
	v_fma_f32 v10, -v6, v9, v8
	v_fmac_f32_e32 v9, v10, v7
	v_fma_f32 v6, -v6, v9, v8
	v_div_fmas_f32 v6, v6, v7, v9
	v_div_fixup_f32 v18, v6, v5, v18
	ds_write_b32 v2, v18 offset:6144
	s_waitcnt vmcnt(60)
	v_mul_f32_e32 v5, 0xbfb8aa3b, v19
	v_exp_f32_e32 v5, v5
	s_nop 0
	v_add_f32_e32 v5, 1.0, v5
	v_div_scale_f32 v6, s[14:15], v5, v5, v19
	v_rcp_f32_e32 v7, v6
	v_div_scale_f32 v8, vcc, v19, v5, v19
	v_fma_f32 v9, -v6, v7, 1.0
	v_fmac_f32_e32 v7, v9, v7
	v_mul_f32_e32 v9, v8, v7
	v_fma_f32 v10, -v6, v9, v8
	v_fmac_f32_e32 v9, v10, v7
	v_fma_f32 v6, -v6, v9, v8
	v_div_fmas_f32 v6, v6, v7, v9
	v_div_fixup_f32 v19, v6, v5, v19
	ds_write_b32 v2, v19 offset:7168
	s_waitcnt vmcnt(59)
	v_mul_f32_e32 v5, 0xbfb8aa3b, v20
	v_exp_f32_e32 v5, v5
	s_nop 0
	v_add_f32_e32 v5, 1.0, v5
	v_div_scale_f32 v6, s[14:15], v5, v5, v20
	v_rcp_f32_e32 v7, v6
	v_div_scale_f32 v8, vcc, v20, v5, v20
	v_fma_f32 v9, -v6, v7, 1.0
	v_fmac_f32_e32 v7, v9, v7
	v_mul_f32_e32 v9, v8, v7
	v_fma_f32 v10, -v6, v9, v8
	v_fmac_f32_e32 v9, v10, v7
	v_fma_f32 v6, -v6, v9, v8
	v_div_fmas_f32 v6, v6, v7, v9
	v_div_fixup_f32 v20, v6, v5, v20
	ds_write_b32 v2, v20 offset:8192
	s_waitcnt vmcnt(58)
	v_mul_f32_e32 v5, 0xbfb8aa3b, v21
	v_exp_f32_e32 v5, v5
	s_nop 0
	v_add_f32_e32 v5, 1.0, v5
	v_div_scale_f32 v6, s[14:15], v5, v5, v21
	v_rcp_f32_e32 v7, v6
	v_div_scale_f32 v8, vcc, v21, v5, v21
	v_fma_f32 v9, -v6, v7, 1.0
	v_fmac_f32_e32 v7, v9, v7
	v_mul_f32_e32 v9, v8, v7
	v_fma_f32 v10, -v6, v9, v8
	v_fmac_f32_e32 v9, v10, v7
	v_fma_f32 v6, -v6, v9, v8
	v_div_fmas_f32 v6, v6, v7, v9
	v_div_fixup_f32 v21, v6, v5, v21
	ds_write_b32 v2, v21 offset:9216
	s_waitcnt vmcnt(57)
	v_mul_f32_e32 v5, 0xbfb8aa3b, v22
	v_exp_f32_e32 v5, v5
	s_nop 0
	v_add_f32_e32 v5, 1.0, v5
	v_div_scale_f32 v6, s[14:15], v5, v5, v22
	v_rcp_f32_e32 v7, v6
	v_div_scale_f32 v8, vcc, v22, v5, v22
	v_fma_f32 v9, -v6, v7, 1.0
	v_fmac_f32_e32 v7, v9, v7
	v_mul_f32_e32 v9, v8, v7
	v_fma_f32 v10, -v6, v9, v8
	v_fmac_f32_e32 v9, v10, v7
	v_fma_f32 v6, -v6, v9, v8
	v_div_fmas_f32 v6, v6, v7, v9
	v_div_fixup_f32 v22, v6, v5, v22
	ds_write_b32 v2, v22 offset:10240
	s_waitcnt vmcnt(56)
	v_mul_f32_e32 v5, 0xbfb8aa3b, v23
	v_exp_f32_e32 v5, v5
	s_nop 0
	v_add_f32_e32 v5, 1.0, v5
	v_div_scale_f32 v6, s[14:15], v5, v5, v23
	v_rcp_f32_e32 v7, v6
	v_div_scale_f32 v8, vcc, v23, v5, v23
	v_fma_f32 v9, -v6, v7, 1.0
	v_fmac_f32_e32 v7, v9, v7
	v_mul_f32_e32 v9, v8, v7
	v_fma_f32 v10, -v6, v9, v8
	v_fmac_f32_e32 v9, v10, v7
	v_fma_f32 v6, -v6, v9, v8
	v_div_fmas_f32 v6, v6, v7, v9
	v_div_fixup_f32 v23, v6, v5, v23
	ds_write_b32 v2, v23 offset:11264
	s_waitcnt vmcnt(55)
	v_mul_f32_e32 v5, 0xbfb8aa3b, v24
	v_exp_f32_e32 v5, v5
	s_nop 0
	v_add_f32_e32 v5, 1.0, v5
	v_div_scale_f32 v6, s[14:15], v5, v5, v24
	v_rcp_f32_e32 v7, v6
	v_div_scale_f32 v8, vcc, v24, v5, v24
	v_fma_f32 v9, -v6, v7, 1.0
	v_fmac_f32_e32 v7, v9, v7
	v_mul_f32_e32 v9, v8, v7
	v_fma_f32 v10, -v6, v9, v8
	v_fmac_f32_e32 v9, v10, v7
	v_fma_f32 v6, -v6, v9, v8
	v_div_fmas_f32 v6, v6, v7, v9
	v_div_fixup_f32 v24, v6, v5, v24
	ds_write_b32 v2, v24 offset:12288
	s_waitcnt vmcnt(54)
	v_mul_f32_e32 v5, 0xbfb8aa3b, v25
	v_exp_f32_e32 v5, v5
	s_nop 0
	v_add_f32_e32 v5, 1.0, v5
	v_div_scale_f32 v6, s[14:15], v5, v5, v25
	v_rcp_f32_e32 v7, v6
	v_div_scale_f32 v8, vcc, v25, v5, v25
	v_fma_f32 v9, -v6, v7, 1.0
	v_fmac_f32_e32 v7, v9, v7
	v_mul_f32_e32 v9, v8, v7
	v_fma_f32 v10, -v6, v9, v8
	v_fmac_f32_e32 v9, v10, v7
	v_fma_f32 v6, -v6, v9, v8
	v_div_fmas_f32 v6, v6, v7, v9
	v_div_fixup_f32 v25, v6, v5, v25
	ds_write_b32 v2, v25 offset:13312
	s_waitcnt vmcnt(53)
	v_mul_f32_e32 v5, 0xbfb8aa3b, v26
	v_exp_f32_e32 v5, v5
	s_nop 0
	v_add_f32_e32 v5, 1.0, v5
	v_div_scale_f32 v6, s[14:15], v5, v5, v26
	v_rcp_f32_e32 v7, v6
	v_div_scale_f32 v8, vcc, v26, v5, v26
	v_fma_f32 v9, -v6, v7, 1.0
	v_fmac_f32_e32 v7, v9, v7
	v_mul_f32_e32 v9, v8, v7
	v_fma_f32 v10, -v6, v9, v8
	v_fmac_f32_e32 v9, v10, v7
	v_fma_f32 v6, -v6, v9, v8
	v_div_fmas_f32 v6, v6, v7, v9
	v_div_fixup_f32 v26, v6, v5, v26
	ds_write_b32 v2, v26 offset:14336
	s_waitcnt vmcnt(52)
; DI float siluf(float x) { return x / (1.f + __expf(-x)); }
; DI void ada_tile(const Params& p, int layer, int cg64, char* lds) {
;     ...
;   for (int e = tid; e < 17 * 1024; e += 256) {
;     int bi = e >> 10, k = e & 1023;
;     float v = bi < 16 ? p.c[bi * 1024 + k] : p.c_ctx[k];
;     sc[e] = siluf(v);
;   }
	v_mul_f32_e32 v5, 0xbfb8aa3b, v27
	v_exp_f32_e32 v5, v5
	s_nop 0
	v_add_f32_e32 v5, 1.0, v5
	v_div_scale_f32 v6, s[14:15], v5, v5, v27
	v_rcp_f32_e32 v7, v6
	v_div_scale_f32 v8, vcc, v27, v5, v27
	v_fma_f32 v9, -v6, v7, 1.0
	v_fmac_f32_e32 v7, v9, v7
	v_mul_f32_e32 v9, v8, v7
	v_fma_f32 v10, -v6, v9, v8
	v_fmac_f32_e32 v9, v10, v7
	v_fma_f32 v6, -v6, v9, v8
	v_div_fmas_f32 v6, v6, v7, v9
	v_div_fixup_f32 v27, v6, v5, v27
	ds_write_b32 v2, v27 offset:15360
	s_waitcnt vmcnt(51)
	v_mul_f32_e32 v5, 0xbfb8aa3b, v28
	v_exp_f32_e32 v5, v5
	s_nop 0
	v_add_f32_e32 v5, 1.0, v5
	v_div_scale_f32 v6, s[14:15], v5, v5, v28
	v_rcp_f32_e32 v7, v6
	v_div_scale_f32 v8, vcc, v28, v5, v28
	v_fma_f32 v9, -v6, v7, 1.0
	v_fmac_f32_e32 v7, v9, v7
	v_mul_f32_e32 v9, v8, v7
	v_fma_f32 v10, -v6, v9, v8
	v_fmac_f32_e32 v9, v10, v7
	v_fma_f32 v6, -v6, v9, v8
	v_div_fmas_f32 v6, v6, v7, v9
	v_div_fixup_f32 v28, v6, v5, v28
	ds_write_b32 v2, v28 offset:16384
	s_waitcnt vmcnt(50)
	v_mul_f32_e32 v5, 0xbfb8aa3b, v29
	v_exp_f32_e32 v5, v5
	s_nop 0
	v_add_f32_e32 v5, 1.0, v5
	v_div_scale_f32 v6, s[14:15], v5, v5, v29
	v_rcp_f32_e32 v7, v6
	v_div_scale_f32 v8, vcc, v29, v5, v29
	v_fma_f32 v9, -v6, v7, 1.0
	v_fmac_f32_e32 v7, v9, v7
	v_mul_f32_e32 v9, v8, v7
	v_fma_f32 v10, -v6, v9, v8
	v_fmac_f32_e32 v9, v10, v7
	v_fma_f32 v6, -v6, v9, v8
	v_div_fmas_f32 v6, v6, v7, v9
	v_div_fixup_f32 v29, v6, v5, v29
	ds_write_b32 v2, v29 offset:17408
	s_waitcnt vmcnt(49)
	v_mul_f32_e32 v5, 0xbfb8aa3b, v30
	v_exp_f32_e32 v5, v5
	s_nop 0
	v_add_f32_e32 v5, 1.0, v5
	v_div_scale_f32 v6, s[14:15], v5, v5, v30
	v_rcp_f32_e32 v7, v6
	v_div_scale_f32 v8, vcc, v30, v5, v30
	v_fma_f32 v9, -v6, v7, 1.0
	v_fmac_f32_e32 v7, v9, v7
	v_mul_f32_e32 v9, v8, v7
	v_fma_f32 v10, -v6, v9, v8
	v_fmac_f32_e32 v9, v10, v7
	v_fma_f32 v6, -v6, v9, v8
	v_div_fmas_f32 v6, v6, v7, v9
	v_div_fixup_f32 v30, v6, v5, v30
	ds_write_b32 v2, v30 offset:18432
	s_waitcnt vmcnt(48)
	v_mul_f32_e32 v5, 0xbfb8aa3b, v31
	v_exp_f32_e32 v5, v5
	s_nop 0
	v_add_f32_e32 v5, 1.0, v5
	v_div_scale_f32 v6, s[14:15], v5, v5, v31
	v_rcp_f32_e32 v7, v6
	v_div_scale_f32 v8, vcc, v31, v5, v31
	v_fma_f32 v9, -v6, v7, 1.0
	v_fmac_f32_e32 v7, v9, v7
	v_mul_f32_e32 v9, v8, v7
	v_fma_f32 v10, -v6, v9, v8
	v_fmac_f32_e32 v9, v10, v7
	v_fma_f32 v6, -v6, v9, v8
	v_div_fmas_f32 v6, v6, v7, v9
	v_div_fixup_f32 v31, v6, v5, v31
	ds_write_b32 v2, v31 offset:19456
	s_waitcnt vmcnt(47)
	v_mul_f32_e32 v5, 0xbfb8aa3b, v32
	v_exp_f32_e32 v5, v5
	s_nop 0
	v_add_f32_e32 v5, 1.0, v5
	v_div_scale_f32 v6, s[14:15], v5, v5, v32
	v_rcp_f32_e32 v7, v6
	v_div_scale_f32 v8, vcc, v32, v5, v32
	v_fma_f32 v9, -v6, v7, 1.0
	v_fmac_f32_e32 v7, v9, v7
	v_mul_f32_e32 v9, v8, v7
	v_fma_f32 v10, -v6, v9, v8
	v_fmac_f32_e32 v9, v10, v7
	v_fma_f32 v6, -v6, v9, v8
	v_div_fmas_f32 v6, v6, v7, v9
	v_div_fixup_f32 v32, v6, v5, v32
	ds_write_b32 v2, v32 offset:20480
	s_waitcnt vmcnt(46)
	v_mul_f32_e32 v5, 0xbfb8aa3b, v33
	v_exp_f32_e32 v5, v5
	s_nop 0
	v_add_f32_e32 v5, 1.0, v5
	v_div_scale_f32 v6, s[14:15], v5, v5, v33
	v_rcp_f32_e32 v7, v6
	v_div_scale_f32 v8, vcc, v33, v5, v33
	v_fma_f32 v9, -v6, v7, 1.0
	v_fmac_f32_e32 v7, v9, v7
	v_mul_f32_e32 v9, v8, v7
	v_fma_f32 v10, -v6, v9, v8
	v_fmac_f32_e32 v9, v10, v7
	v_fma_f32 v6, -v6, v9, v8
	v_div_fmas_f32 v6, v6, v7, v9
	v_div_fixup_f32 v33, v6, v5, v33
	ds_write_b32 v2, v33 offset:21504
	s_waitcnt vmcnt(45)
	v_mul_f32_e32 v5, 0xbfb8aa3b, v34
	v_exp_f32_e32 v5, v5
	s_nop 0
	v_add_f32_e32 v5, 1.0, v5
	v_div_scale_f32 v6, s[14:15], v5, v5, v34
	v_rcp_f32_e32 v7, v6
	v_div_scale_f32 v8, vcc, v34, v5, v34
	v_fma_f32 v9, -v6, v7, 1.0
	v_fmac_f32_e32 v7, v9, v7
	v_mul_f32_e32 v9, v8, v7
	v_fma_f32 v10, -v6, v9, v8
	v_fmac_f32_e32 v9, v10, v7
	v_fma_f32 v6, -v6, v9, v8
	v_div_fmas_f32 v6, v6, v7, v9
	v_div_fixup_f32 v34, v6, v5, v34
	ds_write_b32 v2, v34 offset:22528
	s_waitcnt vmcnt(44)
	v_mul_f32_e32 v5, 0xbfb8aa3b, v35
	v_exp_f32_e32 v5, v5
	s_nop 0
	v_add_f32_e32 v5, 1.0, v5
	v_div_scale_f32 v6, s[14:15], v5, v5, v35
	v_rcp_f32_e32 v7, v6
	v_div_scale_f32 v8, vcc, v35, v5, v35
	v_fma_f32 v9, -v6, v7, 1.0
	v_fmac_f32_e32 v7, v9, v7
	v_mul_f32_e32 v9, v8, v7
	v_fma_f32 v10, -v6, v9, v8
	v_fmac_f32_e32 v9, v10, v7
	v_fma_f32 v6, -v6, v9, v8
	v_div_fmas_f32 v6, v6, v7, v9
	v_div_fixup_f32 v35, v6, v5, v35
	ds_write_b32 v2, v35 offset:23552
	s_waitcnt vmcnt(43)
	v_mul_f32_e32 v5, 0xbfb8aa3b, v36
	v_exp_f32_e32 v5, v5
	s_nop 0
	v_add_f32_e32 v5, 1.0, v5
	v_div_scale_f32 v6, s[14:15], v5, v5, v36
	v_rcp_f32_e32 v7, v6
	v_div_scale_f32 v8, vcc, v36, v5, v36
	v_fma_f32 v9, -v6, v7, 1.0
	v_fmac_f32_e32 v7, v9, v7
	v_mul_f32_e32 v9, v8, v7
	v_fma_f32 v10, -v6, v9, v8
	v_fmac_f32_e32 v9, v10, v7
	v_fma_f32 v6, -v6, v9, v8
	v_div_fmas_f32 v6, v6, v7, v9
	v_div_fixup_f32 v36, v6, v5, v36
	ds_write_b32 v2, v36 offset:24576
	s_waitcnt vmcnt(42)
	v_mul_f32_e32 v5, 0xbfb8aa3b, v37
	v_exp_f32_e32 v5, v5
	s_nop 0
	v_add_f32_e32 v5, 1.0, v5
	v_div_scale_f32 v6, s[14:15], v5, v5, v37
	v_rcp_f32_e32 v7, v6
	v_div_scale_f32 v8, vcc, v37, v5, v37
	v_fma_f32 v9, -v6, v7, 1.0
	v_fmac_f32_e32 v7, v9, v7
	v_mul_f32_e32 v9, v8, v7
	v_fma_f32 v10, -v6, v9, v8
	v_fmac_f32_e32 v9, v10, v7
	v_fma_f32 v6, -v6, v9, v8
	v_div_fmas_f32 v6, v6, v7, v9
	v_div_fixup_f32 v37, v6, v5, v37
	ds_write_b32 v2, v37 offset:25600
	s_waitcnt vmcnt(41)
	v_mul_f32_e32 v5, 0xbfb8aa3b, v38
	v_exp_f32_e32 v5, v5
	s_nop 0
	v_add_f32_e32 v5, 1.0, v5
	v_div_scale_f32 v6, s[14:15], v5, v5, v38
	v_rcp_f32_e32 v7, v6
	v_div_scale_f32 v8, vcc, v38, v5, v38
	v_fma_f32 v9, -v6, v7, 1.0
	v_fmac_f32_e32 v7, v9, v7
	v_mul_f32_e32 v9, v8, v7
	v_fma_f32 v10, -v6, v9, v8
	v_fmac_f32_e32 v9, v10, v7
	v_fma_f32 v6, -v6, v9, v8
	v_div_fmas_f32 v6, v6, v7, v9
	v_div_fixup_f32 v38, v6, v5, v38
	ds_write_b32 v2, v38 offset:26624
	s_waitcnt vmcnt(40)
; DI float siluf(float x) { return x / (1.f + __expf(-x)); }
; DI void ada_tile(const Params& p, int layer, int cg64, char* lds) {
;     ...
;   for (int e = tid; e < 17 * 1024; e += 256) {
;     int bi = e >> 10, k = e & 1023;
;     float v = bi < 16 ? p.c[bi * 1024 + k] : p.c_ctx[k];
;     sc[e] = siluf(v);
;   }
	v_mul_f32_e32 v5, 0xbfb8aa3b, v39
	v_exp_f32_e32 v5, v5
	s_nop 0
	v_add_f32_e32 v5, 1.0, v5
	v_div_scale_f32 v6, s[14:15], v5, v5, v39
	v_rcp_f32_e32 v7, v6
	v_div_scale_f32 v8, vcc, v39, v5, v39
	v_fma_f32 v9, -v6, v7, 1.0
	v_fmac_f32_e32 v7, v9, v7
	v_mul_f32_e32 v9, v8, v7
	v_fma_f32 v10, -v6, v9, v8
	v_fmac_f32_e32 v9, v10, v7
	v_fma_f32 v6, -v6, v9, v8
	v_div_fmas_f32 v6, v6, v7, v9
	v_div_fixup_f32 v39, v6, v5, v39
	ds_write_b32 v2, v39 offset:27648
	s_waitcnt vmcnt(39)
	v_mul_f32_e32 v5, 0xbfb8aa3b, v40
	v_exp_f32_e32 v5, v5
	s_nop 0
	v_add_f32_e32 v5, 1.0, v5
	v_div_scale_f32 v6, s[14:15], v5, v5, v40
	v_rcp_f32_e32 v7, v6
	v_div_scale_f32 v8, vcc, v40, v5, v40
	v_fma_f32 v9, -v6, v7, 1.0
	v_fmac_f32_e32 v7, v9, v7
	v_mul_f32_e32 v9, v8, v7
	v_fma_f32 v10, -v6, v9, v8
	v_fmac_f32_e32 v9, v10, v7
	v_fma_f32 v6, -v6, v9, v8
	v_div_fmas_f32 v6, v6, v7, v9
	v_div_fixup_f32 v40, v6, v5, v40
	ds_write_b32 v2, v40 offset:28672
	s_waitcnt vmcnt(38)
	v_mul_f32_e32 v5, 0xbfb8aa3b, v41
	v_exp_f32_e32 v5, v5
	s_nop 0
	v_add_f32_e32 v5, 1.0, v5
	v_div_scale_f32 v6, s[14:15], v5, v5, v41
	v_rcp_f32_e32 v7, v6
	v_div_scale_f32 v8, vcc, v41, v5, v41
	v_fma_f32 v9, -v6, v7, 1.0
	v_fmac_f32_e32 v7, v9, v7
	v_mul_f32_e32 v9, v8, v7
	v_fma_f32 v10, -v6, v9, v8
	v_fmac_f32_e32 v9, v10, v7
	v_fma_f32 v6, -v6, v9, v8
	v_div_fmas_f32 v6, v6, v7, v9
	v_div_fixup_f32 v41, v6, v5, v41
	ds_write_b32 v2, v41 offset:29696
	s_waitcnt vmcnt(37)
	v_mul_f32_e32 v5, 0xbfb8aa3b, v42
	v_exp_f32_e32 v5, v5
	s_nop 0
	v_add_f32_e32 v5, 1.0, v5
	v_div_scale_f32 v6, s[14:15], v5, v5, v42
	v_rcp_f32_e32 v7, v6
	v_div_scale_f32 v8, vcc, v42, v5, v42
	v_fma_f32 v9, -v6, v7, 1.0
	v_fmac_f32_e32 v7, v9, v7
	v_mul_f32_e32 v9, v8, v7
	v_fma_f32 v10, -v6, v9, v8
	v_fmac_f32_e32 v9, v10, v7
	v_fma_f32 v6, -v6, v9, v8
	v_div_fmas_f32 v6, v6, v7, v9
	v_div_fixup_f32 v42, v6, v5, v42
	ds_write_b32 v2, v42 offset:30720
	s_waitcnt vmcnt(36)
	v_mul_f32_e32 v5, 0xbfb8aa3b, v43
	v_exp_f32_e32 v5, v5
	s_nop 0
	v_add_f32_e32 v5, 1.0, v5
	v_div_scale_f32 v6, s[14:15], v5, v5, v43
	v_rcp_f32_e32 v7, v6
	v_div_scale_f32 v8, vcc, v43, v5, v43
	v_fma_f32 v9, -v6, v7, 1.0
	v_fmac_f32_e32 v7, v9, v7
	v_mul_f32_e32 v9, v8, v7
	v_fma_f32 v10, -v6, v9, v8
	v_fmac_f32_e32 v9, v10, v7
	v_fma_f32 v6, -v6, v9, v8
	v_div_fmas_f32 v6, v6, v7, v9
	v_div_fixup_f32 v43, v6, v5, v43
	ds_write_b32 v2, v43 offset:31744
	s_waitcnt vmcnt(35)
	v_mul_f32_e32 v5, 0xbfb8aa3b, v44
	v_exp_f32_e32 v5, v5
	s_nop 0
	v_add_f32_e32 v5, 1.0, v5
	v_div_scale_f32 v6, s[14:15], v5, v5, v44
	v_rcp_f32_e32 v7, v6
	v_div_scale_f32 v8, vcc, v44, v5, v44
	v_fma_f32 v9, -v6, v7, 1.0
	v_fmac_f32_e32 v7, v9, v7
	v_mul_f32_e32 v9, v8, v7
	v_fma_f32 v10, -v6, v9, v8
	v_fmac_f32_e32 v9, v10, v7
	v_fma_f32 v6, -v6, v9, v8
	v_div_fmas_f32 v6, v6, v7, v9
	v_div_fixup_f32 v44, v6, v5, v44
	ds_write_b32 v2, v44 offset:32768
	s_waitcnt vmcnt(34)
	v_mul_f32_e32 v5, 0xbfb8aa3b, v45
	v_exp_f32_e32 v5, v5
	s_nop 0
	v_add_f32_e32 v5, 1.0, v5
	v_div_scale_f32 v6, s[14:15], v5, v5, v45
	v_rcp_f32_e32 v7, v6
	v_div_scale_f32 v8, vcc, v45, v5, v45
	v_fma_f32 v9, -v6, v7, 1.0
	v_fmac_f32_e32 v7, v9, v7
	v_mul_f32_e32 v9, v8, v7
	v_fma_f32 v10, -v6, v9, v8
	v_fmac_f32_e32 v9, v10, v7
	v_fma_f32 v6, -v6, v9, v8
	v_div_fmas_f32 v6, v6, v7, v9
	v_div_fixup_f32 v45, v6, v5, v45
	ds_write_b32 v2, v45 offset:33792
	s_waitcnt vmcnt(33)
	v_mul_f32_e32 v5, 0xbfb8aa3b, v46
	v_exp_f32_e32 v5, v5
	s_nop 0
	v_add_f32_e32 v5, 1.0, v5
	v_div_scale_f32 v6, s[14:15], v5, v5, v46
	v_rcp_f32_e32 v7, v6
	v_div_scale_f32 v8, vcc, v46, v5, v46
	v_fma_f32 v9, -v6, v7, 1.0
	v_fmac_f32_e32 v7, v9, v7
	v_mul_f32_e32 v9, v8, v7
	v_fma_f32 v10, -v6, v9, v8
	v_fmac_f32_e32 v9, v10, v7
	v_fma_f32 v6, -v6, v9, v8
	v_div_fmas_f32 v6, v6, v7, v9
	v_div_fixup_f32 v46, v6, v5, v46
	ds_write_b32 v2, v46 offset:34816
	s_waitcnt vmcnt(32)
	v_mul_f32_e32 v5, 0xbfb8aa3b, v47
	v_exp_f32_e32 v5, v5
	s_nop 0
	v_add_f32_e32 v5, 1.0, v5
	v_div_scale_f32 v6, s[14:15], v5, v5, v47
	v_rcp_f32_e32 v7, v6
	v_div_scale_f32 v8, vcc, v47, v5, v47
	v_fma_f32 v9, -v6, v7, 1.0
	v_fmac_f32_e32 v7, v9, v7
	v_mul_f32_e32 v9, v8, v7
	v_fma_f32 v10, -v6, v9, v8
	v_fmac_f32_e32 v9, v10, v7
	v_fma_f32 v6, -v6, v9, v8
	v_div_fmas_f32 v6, v6, v7, v9
	v_div_fixup_f32 v47, v6, v5, v47
	ds_write_b32 v2, v47 offset:35840
	s_waitcnt vmcnt(31)
	v_mul_f32_e32 v5, 0xbfb8aa3b, v48
	v_exp_f32_e32 v5, v5
	s_nop 0
	v_add_f32_e32 v5, 1.0, v5
	v_div_scale_f32 v6, s[14:15], v5, v5, v48
	v_rcp_f32_e32 v7, v6
	v_div_scale_f32 v8, vcc, v48, v5, v48
	v_fma_f32 v9, -v6, v7, 1.0
	v_fmac_f32_e32 v7, v9, v7
	v_mul_f32_e32 v9, v8, v7
	v_fma_f32 v10, -v6, v9, v8
	v_fmac_f32_e32 v9, v10, v7
	v_fma_f32 v6, -v6, v9, v8
	v_div_fmas_f32 v6, v6, v7, v9
	v_div_fixup_f32 v48, v6, v5, v48
	ds_write_b32 v2, v48 offset:36864
	s_waitcnt vmcnt(30)
	v_mul_f32_e32 v5, 0xbfb8aa3b, v49
	v_exp_f32_e32 v5, v5
	s_nop 0
	v_add_f32_e32 v5, 1.0, v5
	v_div_scale_f32 v6, s[14:15], v5, v5, v49
	v_rcp_f32_e32 v7, v6
	v_div_scale_f32 v8, vcc, v49, v5, v49
	v_fma_f32 v9, -v6, v7, 1.0
	v_fmac_f32_e32 v7, v9, v7
	v_mul_f32_e32 v9, v8, v7
	v_fma_f32 v10, -v6, v9, v8
	v_fmac_f32_e32 v9, v10, v7
	v_fma_f32 v6, -v6, v9, v8
	v_div_fmas_f32 v6, v6, v7, v9
	v_div_fixup_f32 v49, v6, v5, v49
	ds_write_b32 v2, v49 offset:37888
	s_waitcnt vmcnt(29)
	v_mul_f32_e32 v5, 0xbfb8aa3b, v50
	v_exp_f32_e32 v5, v5
	s_nop 0
	v_add_f32_e32 v5, 1.0, v5
	v_div_scale_f32 v6, s[14:15], v5, v5, v50
	v_rcp_f32_e32 v7, v6
	v_div_scale_f32 v8, vcc, v50, v5, v50
	v_fma_f32 v9, -v6, v7, 1.0
	v_fmac_f32_e32 v7, v9, v7
	v_mul_f32_e32 v9, v8, v7
	v_fma_f32 v10, -v6, v9, v8
	v_fmac_f32_e32 v9, v10, v7
	v_fma_f32 v6, -v6, v9, v8
	v_div_fmas_f32 v6, v6, v7, v9
	v_div_fixup_f32 v50, v6, v5, v50
	ds_write_b32 v2, v50 offset:38912
	s_waitcnt vmcnt(28)
; DI float siluf(float x) { return x / (1.f + __expf(-x)); }
; DI void ada_tile(const Params& p, int layer, int cg64, char* lds) {
;     ...
;   for (int e = tid; e < 17 * 1024; e += 256) {
;     int bi = e >> 10, k = e & 1023;
;     float v = bi < 16 ? p.c[bi * 1024 + k] : p.c_ctx[k];
;     sc[e] = siluf(v);
;   }
	v_mul_f32_e32 v5, 0xbfb8aa3b, v51
	v_exp_f32_e32 v5, v5
	s_nop 0
	v_add_f32_e32 v5, 1.0, v5
	v_div_scale_f32 v6, s[14:15], v5, v5, v51
	v_rcp_f32_e32 v7, v6
	v_div_scale_f32 v8, vcc, v51, v5, v51
	v_fma_f32 v9, -v6, v7, 1.0
	v_fmac_f32_e32 v7, v9, v7
	v_mul_f32_e32 v9, v8, v7
	v_fma_f32 v10, -v6, v9, v8
	v_fmac_f32_e32 v9, v10, v7
	v_fma_f32 v6, -v6, v9, v8
	v_div_fmas_f32 v6, v6, v7, v9
	v_div_fixup_f32 v51, v6, v5, v51
	ds_write_b32 v2, v51 offset:39936
	s_waitcnt vmcnt(27)
	v_mul_f32_e32 v5, 0xbfb8aa3b, v52
	v_exp_f32_e32 v5, v5
	s_nop 0
	v_add_f32_e32 v5, 1.0, v5
	v_div_scale_f32 v6, s[14:15], v5, v5, v52
	v_rcp_f32_e32 v7, v6
	v_div_scale_f32 v8, vcc, v52, v5, v52
	v_fma_f32 v9, -v6, v7, 1.0
	v_fmac_f32_e32 v7, v9, v7
	v_mul_f32_e32 v9, v8, v7
	v_fma_f32 v10, -v6, v9, v8
	v_fmac_f32_e32 v9, v10, v7
	v_fma_f32 v6, -v6, v9, v8
	v_div_fmas_f32 v6, v6, v7, v9
	v_div_fixup_f32 v52, v6, v5, v52
	ds_write_b32 v2, v52 offset:40960
	s_waitcnt vmcnt(26)
	v_mul_f32_e32 v5, 0xbfb8aa3b, v53
	v_exp_f32_e32 v5, v5
	s_nop 0
	v_add_f32_e32 v5, 1.0, v5
	v_div_scale_f32 v6, s[14:15], v5, v5, v53
	v_rcp_f32_e32 v7, v6
	v_div_scale_f32 v8, vcc, v53, v5, v53
	v_fma_f32 v9, -v6, v7, 1.0
	v_fmac_f32_e32 v7, v9, v7
	v_mul_f32_e32 v9, v8, v7
	v_fma_f32 v10, -v6, v9, v8
	v_fmac_f32_e32 v9, v10, v7
	v_fma_f32 v6, -v6, v9, v8
	v_div_fmas_f32 v6, v6, v7, v9
	v_div_fixup_f32 v53, v6, v5, v53
	ds_write_b32 v2, v53 offset:41984
	s_waitcnt vmcnt(25)
	v_mul_f32_e32 v5, 0xbfb8aa3b, v54
	v_exp_f32_e32 v5, v5
	s_nop 0
	v_add_f32_e32 v5, 1.0, v5
	v_div_scale_f32 v6, s[14:15], v5, v5, v54
	v_rcp_f32_e32 v7, v6
	v_div_scale_f32 v8, vcc, v54, v5, v54
	v_fma_f32 v9, -v6, v7, 1.0
	v_fmac_f32_e32 v7, v9, v7
	v_mul_f32_e32 v9, v8, v7
	v_fma_f32 v10, -v6, v9, v8
	v_fmac_f32_e32 v9, v10, v7
	v_fma_f32 v6, -v6, v9, v8
	v_div_fmas_f32 v6, v6, v7, v9
	v_div_fixup_f32 v54, v6, v5, v54
	ds_write_b32 v2, v54 offset:43008
	s_waitcnt vmcnt(24)
	v_mul_f32_e32 v5, 0xbfb8aa3b, v55
	v_exp_f32_e32 v5, v5
	s_nop 0
	v_add_f32_e32 v5, 1.0, v5
	v_div_scale_f32 v6, s[14:15], v5, v5, v55
	v_rcp_f32_e32 v7, v6
	v_div_scale_f32 v8, vcc, v55, v5, v55
	v_fma_f32 v9, -v6, v7, 1.0
	v_fmac_f32_e32 v7, v9, v7
	v_mul_f32_e32 v9, v8, v7
	v_fma_f32 v10, -v6, v9, v8
	v_fmac_f32_e32 v9, v10, v7
	v_fma_f32 v6, -v6, v9, v8
	v_div_fmas_f32 v6, v6, v7, v9
	v_div_fixup_f32 v55, v6, v5, v55
	ds_write_b32 v2, v55 offset:44032
	s_waitcnt vmcnt(23)
	v_mul_f32_e32 v5, 0xbfb8aa3b, v56
	v_exp_f32_e32 v5, v5
	s_nop 0
	v_add_f32_e32 v5, 1.0, v5
	v_div_scale_f32 v6, s[14:15], v5, v5, v56
	v_rcp_f32_e32 v7, v6
	v_div_scale_f32 v8, vcc, v56, v5, v56
	v_fma_f32 v9, -v6, v7, 1.0
	v_fmac_f32_e32 v7, v9, v7
	v_mul_f32_e32 v9, v8, v7
	v_fma_f32 v10, -v6, v9, v8
	v_fmac_f32_e32 v9, v10, v7
	v_fma_f32 v6, -v6, v9, v8
	v_div_fmas_f32 v6, v6, v7, v9
	v_div_fixup_f32 v56, v6, v5, v56
	ds_write_b32 v2, v56 offset:45056
	s_waitcnt vmcnt(22)
	v_mul_f32_e32 v5, 0xbfb8aa3b, v57
	v_exp_f32_e32 v5, v5
	s_nop 0
	v_add_f32_e32 v5, 1.0, v5
	v_div_scale_f32 v6, s[14:15], v5, v5, v57
	v_rcp_f32_e32 v7, v6
	v_div_scale_f32 v8, vcc, v57, v5, v57
	v_fma_f32 v9, -v6, v7, 1.0
	v_fmac_f32_e32 v7, v9, v7
	v_mul_f32_e32 v9, v8, v7
	v_fma_f32 v10, -v6, v9, v8
	v_fmac_f32_e32 v9, v10, v7
	v_fma_f32 v6, -v6, v9, v8
	v_div_fmas_f32 v6, v6, v7, v9
	v_div_fixup_f32 v57, v6, v5, v57
	ds_write_b32 v2, v57 offset:46080
	s_waitcnt vmcnt(21)
	v_mul_f32_e32 v5, 0xbfb8aa3b, v58
	v_exp_f32_e32 v5, v5
	s_nop 0
	v_add_f32_e32 v5, 1.0, v5
	v_div_scale_f32 v6, s[14:15], v5, v5, v58
	v_rcp_f32_e32 v7, v6
	v_div_scale_f32 v8, vcc, v58, v5, v58
	v_fma_f32 v9, -v6, v7, 1.0
	v_fmac_f32_e32 v7, v9, v7
	v_mul_f32_e32 v9, v8, v7
	v_fma_f32 v10, -v6, v9, v8
	v_fmac_f32_e32 v9, v10, v7
	v_fma_f32 v6, -v6, v9, v8
	v_div_fmas_f32 v6, v6, v7, v9
	v_div_fixup_f32 v58, v6, v5, v58
	ds_write_b32 v2, v58 offset:47104
	s_waitcnt vmcnt(20)
	v_mul_f32_e32 v5, 0xbfb8aa3b, v59
	v_exp_f32_e32 v5, v5
	s_nop 0
	v_add_f32_e32 v5, 1.0, v5
	v_div_scale_f32 v6, s[14:15], v5, v5, v59
	v_rcp_f32_e32 v7, v6
	v_div_scale_f32 v8, vcc, v59, v5, v59
	v_fma_f32 v9, -v6, v7, 1.0
	v_fmac_f32_e32 v7, v9, v7
	v_mul_f32_e32 v9, v8, v7
	v_fma_f32 v10, -v6, v9, v8
	v_fmac_f32_e32 v9, v10, v7
	v_fma_f32 v6, -v6, v9, v8
	v_div_fmas_f32 v6, v6, v7, v9
	v_div_fixup_f32 v59, v6, v5, v59
	ds_write_b32 v2, v59 offset:48128
	s_waitcnt vmcnt(19)
	v_mul_f32_e32 v5, 0xbfb8aa3b, v60
	v_exp_f32_e32 v5, v5
	s_nop 0
	v_add_f32_e32 v5, 1.0, v5
	v_div_scale_f32 v6, s[14:15], v5, v5, v60
	v_rcp_f32_e32 v7, v6
	v_div_scale_f32 v8, vcc, v60, v5, v60
	v_fma_f32 v9, -v6, v7, 1.0
	v_fmac_f32_e32 v7, v9, v7
	v_mul_f32_e32 v9, v8, v7
	v_fma_f32 v10, -v6, v9, v8
	v_fmac_f32_e32 v9, v10, v7
	v_fma_f32 v6, -v6, v9, v8
	v_div_fmas_f32 v6, v6, v7, v9
	v_div_fixup_f32 v60, v6, v5, v60
	ds_write_b32 v2, v60 offset:49152
	s_waitcnt vmcnt(18)
	v_mul_f32_e32 v5, 0xbfb8aa3b, v61
	v_exp_f32_e32 v5, v5
	s_nop 0
	v_add_f32_e32 v5, 1.0, v5
	v_div_scale_f32 v6, s[14:15], v5, v5, v61
	v_rcp_f32_e32 v7, v6
	v_div_scale_f32 v8, vcc, v61, v5, v61
	v_fma_f32 v9, -v6, v7, 1.0
	v_fmac_f32_e32 v7, v9, v7
	v_mul_f32_e32 v9, v8, v7
	v_fma_f32 v10, -v6, v9, v8
	v_fmac_f32_e32 v9, v10, v7
	v_fma_f32 v6, -v6, v9, v8
	v_div_fmas_f32 v6, v6, v7, v9
	v_div_fixup_f32 v61, v6, v5, v61
	ds_write_b32 v2, v61 offset:50176
	s_waitcnt vmcnt(17)
	v_mul_f32_e32 v5, 0xbfb8aa3b, v62
	v_exp_f32_e32 v5, v5
	s_nop 0
	v_add_f32_e32 v5, 1.0, v5
	v_div_scale_f32 v6, s[14:15], v5, v5, v62
	v_rcp_f32_e32 v7, v6
	v_div_scale_f32 v8, vcc, v62, v5, v62
	v_fma_f32 v9, -v6, v7, 1.0
	v_fmac_f32_e32 v7, v9, v7
	v_mul_f32_e32 v9, v8, v7
	v_fma_f32 v10, -v6, v9, v8
	v_fmac_f32_e32 v9, v10, v7
	v_fma_f32 v6, -v6, v9, v8
	v_div_fmas_f32 v6, v6, v7, v9
	v_div_fixup_f32 v62, v6, v5, v62
	ds_write_b32 v2, v62 offset:51200
	s_waitcnt vmcnt(16)
; DI float siluf(float x) { return x / (1.f + __expf(-x)); }
; DI void ada_tile(const Params& p, int layer, int cg64, char* lds) {
;     ...
;   for (int e = tid; e < 17 * 1024; e += 256) {
;     int bi = e >> 10, k = e & 1023;
;     float v = bi < 16 ? p.c[bi * 1024 + k] : p.c_ctx[k];
;     sc[e] = siluf(v);
;   }
	v_mul_f32_e32 v5, 0xbfb8aa3b, v63
	v_exp_f32_e32 v5, v5
	s_nop 0
	v_add_f32_e32 v5, 1.0, v5
	v_div_scale_f32 v6, s[14:15], v5, v5, v63
	v_rcp_f32_e32 v7, v6
	v_div_scale_f32 v8, vcc, v63, v5, v63
	v_fma_f32 v9, -v6, v7, 1.0
	v_fmac_f32_e32 v7, v9, v7
	v_mul_f32_e32 v9, v8, v7
	v_fma_f32 v10, -v6, v9, v8
	v_fmac_f32_e32 v9, v10, v7
	v_fma_f32 v6, -v6, v9, v8
	v_div_fmas_f32 v6, v6, v7, v9
	v_div_fixup_f32 v63, v6, v5, v63
	ds_write_b32 v2, v63 offset:52224
	s_waitcnt vmcnt(15)
	v_mul_f32_e32 v5, 0xbfb8aa3b, v64
	v_exp_f32_e32 v5, v5
	s_nop 0
	v_add_f32_e32 v5, 1.0, v5
	v_div_scale_f32 v6, s[14:15], v5, v5, v64
	v_rcp_f32_e32 v7, v6
	v_div_scale_f32 v8, vcc, v64, v5, v64
	v_fma_f32 v9, -v6, v7, 1.0
	v_fmac_f32_e32 v7, v9, v7
	v_mul_f32_e32 v9, v8, v7
	v_fma_f32 v10, -v6, v9, v8
	v_fmac_f32_e32 v9, v10, v7
	v_fma_f32 v6, -v6, v9, v8
	v_div_fmas_f32 v6, v6, v7, v9
	v_div_fixup_f32 v64, v6, v5, v64
	ds_write_b32 v2, v64 offset:53248
	s_waitcnt vmcnt(14)
	v_mul_f32_e32 v5, 0xbfb8aa3b, v65
	v_exp_f32_e32 v5, v5
	s_nop 0
	v_add_f32_e32 v5, 1.0, v5
	v_div_scale_f32 v6, s[14:15], v5, v5, v65
	v_rcp_f32_e32 v7, v6
	v_div_scale_f32 v8, vcc, v65, v5, v65
	v_fma_f32 v9, -v6, v7, 1.0
	v_fmac_f32_e32 v7, v9, v7
	v_mul_f32_e32 v9, v8, v7
	v_fma_f32 v10, -v6, v9, v8
	v_fmac_f32_e32 v9, v10, v7
	v_fma_f32 v6, -v6, v9, v8
	v_div_fmas_f32 v6, v6, v7, v9
	v_div_fixup_f32 v65, v6, v5, v65
	ds_write_b32 v2, v65 offset:54272
	s_waitcnt vmcnt(13)
	v_mul_f32_e32 v5, 0xbfb8aa3b, v66
	v_exp_f32_e32 v5, v5
	s_nop 0
	v_add_f32_e32 v5, 1.0, v5
	v_div_scale_f32 v6, s[14:15], v5, v5, v66
	v_rcp_f32_e32 v7, v6
	v_div_scale_f32 v8, vcc, v66, v5, v66
	v_fma_f32 v9, -v6, v7, 1.0
	v_fmac_f32_e32 v7, v9, v7
	v_mul_f32_e32 v9, v8, v7
	v_fma_f32 v10, -v6, v9, v8
	v_fmac_f32_e32 v9, v10, v7
	v_fma_f32 v6, -v6, v9, v8
	v_div_fmas_f32 v6, v6, v7, v9
	v_div_fixup_f32 v66, v6, v5, v66
	ds_write_b32 v2, v66 offset:55296
	s_waitcnt vmcnt(12)
	v_mul_f32_e32 v5, 0xbfb8aa3b, v67
	v_exp_f32_e32 v5, v5
	s_nop 0
	v_add_f32_e32 v5, 1.0, v5
	v_div_scale_f32 v6, s[14:15], v5, v5, v67
	v_rcp_f32_e32 v7, v6
	v_div_scale_f32 v8, vcc, v67, v5, v67
	v_fma_f32 v9, -v6, v7, 1.0
	v_fmac_f32_e32 v7, v9, v7
	v_mul_f32_e32 v9, v8, v7
	v_fma_f32 v10, -v6, v9, v8
	v_fmac_f32_e32 v9, v10, v7
	v_fma_f32 v6, -v6, v9, v8
	v_div_fmas_f32 v6, v6, v7, v9
	v_div_fixup_f32 v67, v6, v5, v67
	ds_write_b32 v2, v67 offset:56320
	s_waitcnt vmcnt(11)
	v_mul_f32_e32 v5, 0xbfb8aa3b, v68
	v_exp_f32_e32 v5, v5
	s_nop 0
	v_add_f32_e32 v5, 1.0, v5
	v_div_scale_f32 v6, s[14:15], v5, v5, v68
	v_rcp_f32_e32 v7, v6
	v_div_scale_f32 v8, vcc, v68, v5, v68
	v_fma_f32 v9, -v6, v7, 1.0
	v_fmac_f32_e32 v7, v9, v7
	v_mul_f32_e32 v9, v8, v7
	v_fma_f32 v10, -v6, v9, v8
	v_fmac_f32_e32 v9, v10, v7
	v_fma_f32 v6, -v6, v9, v8
	v_div_fmas_f32 v6, v6, v7, v9
	v_div_fixup_f32 v68, v6, v5, v68
	ds_write_b32 v2, v68 offset:57344
	s_waitcnt vmcnt(10)
	v_mul_f32_e32 v5, 0xbfb8aa3b, v69
	v_exp_f32_e32 v5, v5
	s_nop 0
	v_add_f32_e32 v5, 1.0, v5
	v_div_scale_f32 v6, s[14:15], v5, v5, v69
	v_rcp_f32_e32 v7, v6
	v_div_scale_f32 v8, vcc, v69, v5, v69
	v_fma_f32 v9, -v6, v7, 1.0
	v_fmac_f32_e32 v7, v9, v7
	v_mul_f32_e32 v9, v8, v7
	v_fma_f32 v10, -v6, v9, v8
	v_fmac_f32_e32 v9, v10, v7
	v_fma_f32 v6, -v6, v9, v8
	v_div_fmas_f32 v6, v6, v7, v9
	v_div_fixup_f32 v69, v6, v5, v69
	ds_write_b32 v2, v69 offset:58368
	s_waitcnt vmcnt(9)
	v_mul_f32_e32 v5, 0xbfb8aa3b, v70
	v_exp_f32_e32 v5, v5
	s_nop 0
	v_add_f32_e32 v5, 1.0, v5
	v_div_scale_f32 v6, s[14:15], v5, v5, v70
	v_rcp_f32_e32 v7, v6
	v_div_scale_f32 v8, vcc, v70, v5, v70
	v_fma_f32 v9, -v6, v7, 1.0
	v_fmac_f32_e32 v7, v9, v7
	v_mul_f32_e32 v9, v8, v7
	v_fma_f32 v10, -v6, v9, v8
	v_fmac_f32_e32 v9, v10, v7
	v_fma_f32 v6, -v6, v9, v8
	v_div_fmas_f32 v6, v6, v7, v9
	v_div_fixup_f32 v70, v6, v5, v70
	ds_write_b32 v2, v70 offset:59392
	s_waitcnt vmcnt(8)
	v_mul_f32_e32 v5, 0xbfb8aa3b, v71
	v_exp_f32_e32 v5, v5
	s_nop 0
	v_add_f32_e32 v5, 1.0, v5
	v_div_scale_f32 v6, s[14:15], v5, v5, v71
	v_rcp_f32_e32 v7, v6
	v_div_scale_f32 v8, vcc, v71, v5, v71
	v_fma_f32 v9, -v6, v7, 1.0
	v_fmac_f32_e32 v7, v9, v7
	v_mul_f32_e32 v9, v8, v7
	v_fma_f32 v10, -v6, v9, v8
	v_fmac_f32_e32 v9, v10, v7
	v_fma_f32 v6, -v6, v9, v8
	v_div_fmas_f32 v6, v6, v7, v9
	v_div_fixup_f32 v71, v6, v5, v71
	ds_write_b32 v2, v71 offset:60416
	s_waitcnt vmcnt(7)
; DI float siluf(float x) { return x / (1.f + __expf(-x)); }
; DI void ada_tile(const Params& p, int layer, int cg64, char* lds) {
;     ...
;   for (int e = tid; e < 17 * 1024; e += 256) {
;     int bi = e >> 10, k = e & 1023;
;     float v = bi < 16 ? p.c[bi * 1024 + k] : p.c_ctx[k];
;     sc[e] = siluf(v);
;   }
	v_mul_f32_e32 v5, 0xbfb8aa3b, v98
	v_exp_f32_e32 v5, v5
	s_nop 0
	v_add_f32_e32 v5, 1.0, v5
	v_div_scale_f32 v6, s[14:15], v5, v5, v98
	v_rcp_f32_e32 v7, v6
	v_div_scale_f32 v8, vcc, v98, v5, v98
	v_fma_f32 v9, -v6, v7, 1.0
	v_fmac_f32_e32 v7, v9, v7
	v_mul_f32_e32 v9, v8, v7
	v_fma_f32 v10, -v6, v9, v8
	v_fmac_f32_e32 v9, v10, v7
	v_fma_f32 v6, -v6, v9, v8
	v_div_fmas_f32 v6, v6, v7, v9
	v_div_fixup_f32 v98, v6, v5, v98
	ds_write_b32 v2, v98 offset:61440
	s_waitcnt vmcnt(6)
	v_mul_f32_e32 v5, 0xbfb8aa3b, v99
	v_exp_f32_e32 v5, v5
	s_nop 0
	v_add_f32_e32 v5, 1.0, v5
	v_div_scale_f32 v6, s[14:15], v5, v5, v99
	v_rcp_f32_e32 v7, v6
	v_div_scale_f32 v8, vcc, v99, v5, v99
	v_fma_f32 v9, -v6, v7, 1.0
	v_fmac_f32_e32 v7, v9, v7
	v_mul_f32_e32 v9, v8, v7
	v_fma_f32 v10, -v6, v9, v8
	v_fmac_f32_e32 v9, v10, v7
	v_fma_f32 v6, -v6, v9, v8
	v_div_fmas_f32 v6, v6, v7, v9
	v_div_fixup_f32 v99, v6, v5, v99
	ds_write_b32 v2, v99 offset:62464
	s_waitcnt vmcnt(5)
	v_mul_f32_e32 v5, 0xbfb8aa3b, v100
	v_exp_f32_e32 v5, v5
	s_nop 0
	v_add_f32_e32 v5, 1.0, v5
	v_div_scale_f32 v6, s[14:15], v5, v5, v100
	v_rcp_f32_e32 v7, v6
	v_div_scale_f32 v8, vcc, v100, v5, v100
	v_fma_f32 v9, -v6, v7, 1.0
	v_fmac_f32_e32 v7, v9, v7
	v_mul_f32_e32 v9, v8, v7
	v_fma_f32 v10, -v6, v9, v8
	v_fmac_f32_e32 v9, v10, v7
	v_fma_f32 v6, -v6, v9, v8
	v_div_fmas_f32 v6, v6, v7, v9
	v_div_fixup_f32 v100, v6, v5, v100
	ds_write_b32 v2, v100 offset:63488
	s_waitcnt vmcnt(4)
	v_mul_f32_e32 v5, 0xbfb8aa3b, v101
	v_exp_f32_e32 v5, v5
	s_nop 0
	v_add_f32_e32 v5, 1.0, v5
	v_div_scale_f32 v6, s[14:15], v5, v5, v101
	v_rcp_f32_e32 v7, v6
	v_div_scale_f32 v8, vcc, v101, v5, v101
	v_fma_f32 v9, -v6, v7, 1.0
	v_fmac_f32_e32 v7, v9, v7
	v_mul_f32_e32 v9, v8, v7
	v_fma_f32 v10, -v6, v9, v8
	v_fmac_f32_e32 v9, v10, v7
	v_fma_f32 v6, -v6, v9, v8
	v_div_fmas_f32 v6, v6, v7, v9
	v_div_fixup_f32 v101, v6, v5, v101
	ds_write_b32 v2, v101 offset:64512
	s_waitcnt vmcnt(3)
	v_mul_f32_e32 v5, 0xbfb8aa3b, v102
	v_exp_f32_e32 v5, v5
	s_nop 0
	v_add_f32_e32 v5, 1.0, v5
	v_div_scale_f32 v6, s[14:15], v5, v5, v102
	v_rcp_f32_e32 v7, v6
	v_div_scale_f32 v8, vcc, v102, v5, v102
	v_fma_f32 v9, -v6, v7, 1.0
	v_fmac_f32_e32 v7, v9, v7
	v_mul_f32_e32 v9, v8, v7
	v_fma_f32 v10, -v6, v9, v8
	v_fmac_f32_e32 v9, v10, v7
	v_fma_f32 v6, -v6, v9, v8
	v_div_fmas_f32 v6, v6, v7, v9
	v_div_fixup_f32 v102, v6, v5, v102
	ds_write_b32 v11, v102
	s_waitcnt vmcnt(2)
	v_mul_f32_e32 v5, 0xbfb8aa3b, v103
	v_exp_f32_e32 v5, v5
	s_nop 0
	v_add_f32_e32 v5, 1.0, v5
	v_div_scale_f32 v6, s[14:15], v5, v5, v103
	v_rcp_f32_e32 v7, v6
	v_div_scale_f32 v8, vcc, v103, v5, v103
	v_fma_f32 v9, -v6, v7, 1.0
	v_fmac_f32_e32 v7, v9, v7
	v_mul_f32_e32 v9, v8, v7
	v_fma_f32 v10, -v6, v9, v8
	v_fmac_f32_e32 v9, v10, v7
	v_fma_f32 v6, -v6, v9, v8
	v_div_fmas_f32 v6, v6, v7, v9
	v_div_fixup_f32 v103, v6, v5, v103
	ds_write_b32 v11, v103 offset:1024
	s_waitcnt vmcnt(1)
	v_mul_f32_e32 v5, 0xbfb8aa3b, v104
	v_exp_f32_e32 v5, v5
	s_nop 0
	v_add_f32_e32 v5, 1.0, v5
	v_div_scale_f32 v6, s[14:15], v5, v5, v104
	v_rcp_f32_e32 v7, v6
	v_div_scale_f32 v8, vcc, v104, v5, v104
	v_fma_f32 v9, -v6, v7, 1.0
	v_fmac_f32_e32 v7, v9, v7
	v_mul_f32_e32 v9, v8, v7
	v_fma_f32 v10, -v6, v9, v8
	v_fmac_f32_e32 v9, v10, v7
	v_fma_f32 v6, -v6, v9, v8
	v_div_fmas_f32 v6, v6, v7, v9
	v_div_fixup_f32 v104, v6, v5, v104
	ds_write_b32 v11, v104 offset:2048
	s_waitcnt vmcnt(0)
	v_mul_f32_e32 v5, 0xbfb8aa3b, v105
	v_exp_f32_e32 v5, v5
	s_nop 0
	v_add_f32_e32 v5, 1.0, v5
	v_div_scale_f32 v6, s[14:15], v5, v5, v105
	v_rcp_f32_e32 v7, v6
	v_div_scale_f32 v8, vcc, v105, v5, v105
	v_fma_f32 v9, -v6, v7, 1.0
	v_fmac_f32_e32 v7, v9, v7
	v_mul_f32_e32 v9, v8, v7
	v_fma_f32 v10, -v6, v9, v8
	v_fmac_f32_e32 v9, v10, v7
	v_fma_f32 v6, -v6, v9, v8
	v_div_fmas_f32 v6, v6, v7, v9
	v_div_fixup_f32 v105, v6, v5, v105
	ds_write_b32 v11, v105 offset:3072

; DI void prep_mla(const Params& p, int layer, int tm, int which, int nt, char* lds) {
;     ...
;     for (int i = 0; i < KK / 8; i += 4) {
;       u32x4 u0 = ldg16(src + i * 8), u1 = ldg16(src + i * 8 + 8), u2 = ldg16(src + i * 8 + 16), u3 = ldg16(src + i * 8 + 24);
;       float f[8];
;       unpack8(u0, f);
; #pragma unroll
;       for (int e = 0; e < 8; ++e) s += f[e] * f[e];
;       unpack8(u1, f);
; #pragma unroll
;       for (int e = 0; e < 8; ++e) s += f[e] * f[e];
;       unpack8(u2, f);
; #pragma unroll
;       for (int e = 0; e < 8; ++e) s += f[e] * f[e];
;       unpack8(u3, f);
; #pragma unroll
;       for (int e = 0; e < 8; ++e) s += f[e] * f[e];
;     }
;     rs[tid] = rsqrtf(s / (float)KK + 1e-6f);
.LBB0_225:
	global_load_dwordx4 v[4:7], v[2:3], off offset:48
	global_load_dwordx4 v[8:11], v[2:3], off offset:32
	global_load_dwordx4 v[12:15], v[2:3], off offset:16
	global_load_dwordx4 v[16:19], v[2:3], off offset:0
	global_load_dwordx4 v[20:23], v[2:3], off offset:112
	global_load_dwordx4 v[24:27], v[2:3], off offset:96
	global_load_dwordx4 v[28:31], v[2:3], off offset:80
	global_load_dwordx4 v[32:35], v[2:3], off offset:64
	global_load_dwordx4 v[36:39], v[2:3], off offset:176
	global_load_dwordx4 v[40:43], v[2:3], off offset:160
	global_load_dwordx4 v[44:47], v[2:3], off offset:144
	global_load_dwordx4 v[48:51], v[2:3], off offset:128
	global_load_dwordx4 v[52:55], v[2:3], off offset:240
	global_load_dwordx4 v[56:59], v[2:3], off offset:224
	global_load_dwordx4 v[60:63], v[2:3], off offset:208
	global_load_dwordx4 v[64:67], v[2:3], off offset:192
	s_waitcnt vmcnt(12)
	v_lshlrev_b32_e32 v132, 16, v16
	v_and_b32_e32 v16, 0xffff0000, v16
	v_fmac_f32_e32 v0, v132, v132
	v_lshlrev_b32_e32 v133, 16, v17
	v_fmac_f32_e32 v0, v16, v16
	v_and_b32_e32 v17, 0xffff0000, v17
	v_fmac_f32_e32 v0, v133, v133
	v_lshlrev_b32_e32 v134, 16, v18
	v_fmac_f32_e32 v0, v17, v17
	v_and_b32_e32 v18, 0xffff0000, v18
	v_fmac_f32_e32 v0, v134, v134
	v_lshlrev_b32_e32 v135, 16, v19
	v_fmac_f32_e32 v0, v18, v18
	v_and_b32_e32 v19, 0xffff0000, v19
	v_fmac_f32_e32 v0, v135, v135
	v_fmac_f32_e32 v0, v19, v19
	v_lshlrev_b32_e32 v16, 16, v12
	v_and_b32_e32 v12, 0xffff0000, v12
	v_fmac_f32_e32 v0, v16, v16
	v_lshlrev_b32_e32 v17, 16, v13
	v_fmac_f32_e32 v0, v12, v12
	v_and_b32_e32 v13, 0xffff0000, v13
	v_fmac_f32_e32 v0, v17, v17
	v_lshlrev_b32_e32 v18, 16, v14
	v_fmac_f32_e32 v0, v13, v13
	v_and_b32_e32 v14, 0xffff0000, v14
	v_fmac_f32_e32 v0, v18, v18
	v_lshlrev_b32_e32 v19, 16, v15
	v_fmac_f32_e32 v0, v14, v14
	v_and_b32_e32 v15, 0xffff0000, v15
	v_fmac_f32_e32 v0, v19, v19
	v_fmac_f32_e32 v0, v15, v15
	v_lshlrev_b32_e32 v12, 16, v8
	v_and_b32_e32 v8, 0xffff0000, v8
	v_fmac_f32_e32 v0, v12, v12
	v_lshlrev_b32_e32 v13, 16, v9
	v_fmac_f32_e32 v0, v8, v8
	v_fmac_f32_e32 v0, v13, v13
	v_lshlrev_b32_e32 v13, 16, v10
	v_and_b32_e32 v12, 0xffff0000, v9
	v_pk_mul_f32 v[8:9], v[12:13], v[12:13]
	s_nop 0
	v_add_f32_e32 v0, v8, v0
	v_add_f32_e32 v0, v9, v0
	v_lshlrev_b32_e32 v9, 16, v11
	v_and_b32_e32 v8, 0xffff0000, v10
	v_pk_mul_f32 v[8:9], v[8:9], v[8:9]
	v_and_b32_e32 v10, 0xffff0000, v7
	v_add_f32_e32 v0, v8, v0
	v_add_f32_e32 v0, v9, v0
	v_lshlrev_b32_e32 v8, 16, v4
	v_and_b32_e32 v9, 0xffff0000, v11
	v_pk_mul_f32 v[8:9], v[8:9], v[8:9]
	s_nop 0
	v_add_f32_e32 v0, v9, v0
	v_add_f32_e32 v0, v8, v0
	v_lshlrev_b32_e32 v9, 16, v5
	v_and_b32_e32 v8, 0xffff0000, v4
	v_pk_mul_f32 v[8:9], v[8:9], v[8:9]
	s_nop 0
	v_add_f32_e32 v0, v8, v0
	v_add_f32_e32 v0, v9, v0
	v_lshlrev_b32_e32 v9, 16, v6
	v_and_b32_e32 v8, 0xffff0000, v5
	v_pk_mul_f32 v[4:5], v[8:9], v[8:9]
	s_nop 0
	v_add_f32_e32 v0, v4, v0
	v_add_f32_e32 v0, v5, v0
	v_lshlrev_b32_e32 v5, 16, v7
	v_and_b32_e32 v4, 0xffff0000, v6
	v_pk_mul_f32 v[4:5], v[4:5], v[4:5]
	s_nop 0
	v_add_f32_e32 v0, v4, v0
	v_add_f32_e32 v0, v5, v0
	v_fmac_f32_e32 v0, v10, v10
	s_waitcnt vmcnt(8)
	v_lshlrev_b32_e32 v132, 16, v32
	v_and_b32_e32 v32, 0xffff0000, v32
	v_fmac_f32_e32 v0, v132, v132
	v_lshlrev_b32_e32 v133, 16, v33
	v_fmac_f32_e32 v0, v32, v32
	v_and_b32_e32 v33, 0xffff0000, v33
	v_fmac_f32_e32 v0, v133, v133
	v_lshlrev_b32_e32 v134, 16, v34
	v_fmac_f32_e32 v0, v33, v33
	v_and_b32_e32 v34, 0xffff0000, v34
	v_fmac_f32_e32 v0, v134, v134
	v_lshlrev_b32_e32 v135, 16, v35
	v_fmac_f32_e32 v0, v34, v34
	v_and_b32_e32 v35, 0xffff0000, v35
	v_fmac_f32_e32 v0, v135, v135
	v_fmac_f32_e32 v0, v35, v35
	v_lshlrev_b32_e32 v32, 16, v28
	v_and_b32_e32 v28, 0xffff0000, v28
	v_fmac_f32_e32 v0, v32, v32
	v_lshlrev_b32_e32 v33, 16, v29
	v_fmac_f32_e32 v0, v28, v28
	v_and_b32_e32 v29, 0xffff0000, v29
	v_fmac_f32_e32 v0, v33, v33
	v_lshlrev_b32_e32 v34, 16, v30
	v_fmac_f32_e32 v0, v29, v29
	v_and_b32_e32 v30, 0xffff0000, v30
	v_fmac_f32_e32 v0, v34, v34
	v_lshlrev_b32_e32 v35, 16, v31
	v_fmac_f32_e32 v0, v30, v30
	v_and_b32_e32 v31, 0xffff0000, v31
	v_fmac_f32_e32 v0, v35, v35
	v_fmac_f32_e32 v0, v31, v31
	v_lshlrev_b32_e32 v28, 16, v24
	v_and_b32_e32 v24, 0xffff0000, v24
	v_fmac_f32_e32 v0, v28, v28
	v_lshlrev_b32_e32 v29, 16, v25
	v_fmac_f32_e32 v0, v24, v24
	v_fmac_f32_e32 v0, v29, v29
	v_lshlrev_b32_e32 v29, 16, v26
	v_and_b32_e32 v28, 0xffff0000, v25
	v_pk_mul_f32 v[24:25], v[28:29], v[28:29]
	s_nop 0
	v_add_f32_e32 v0, v24, v0
	v_add_f32_e32 v0, v25, v0
	v_lshlrev_b32_e32 v25, 16, v27
	v_and_b32_e32 v24, 0xffff0000, v26
	v_pk_mul_f32 v[24:25], v[24:25], v[24:25]
	v_and_b32_e32 v26, 0xffff0000, v23
	v_add_f32_e32 v0, v24, v0
	v_add_f32_e32 v0, v25, v0
	v_lshlrev_b32_e32 v24, 16, v20
	v_and_b32_e32 v25, 0xffff0000, v27
	v_pk_mul_f32 v[24:25], v[24:25], v[24:25]
	s_nop 0
	v_add_f32_e32 v0, v25, v0
	v_add_f32_e32 v0, v24, v0
	v_lshlrev_b32_e32 v25, 16, v21
	v_and_b32_e32 v24, 0xffff0000, v20
	v_pk_mul_f32 v[24:25], v[24:25], v[24:25]
	s_nop 0
	v_add_f32_e32 v0, v24, v0
	v_add_f32_e32 v0, v25, v0
	v_lshlrev_b32_e32 v25, 16, v22
	v_and_b32_e32 v24, 0xffff0000, v21
	v_pk_mul_f32 v[20:21], v[24:25], v[24:25]
	s_nop 0
	v_add_f32_e32 v0, v20, v0
	v_add_f32_e32 v0, v21, v0
	v_lshlrev_b32_e32 v21, 16, v23
	v_and_b32_e32 v20, 0xffff0000, v22
	v_pk_mul_f32 v[20:21], v[20:21], v[20:21]
	s_nop 0
	v_add_f32_e32 v0, v20, v0
	v_add_f32_e32 v0, v21, v0
	v_fmac_f32_e32 v0, v26, v26
	s_waitcnt vmcnt(4)
; DI void prep_mla(const Params& p, int layer, int tm, int which, int nt, char* lds) {
;     ...
;     for (int i = 0; i < KK / 8; i += 4) {
;       u32x4 u0 = ldg16(src + i * 8), u1 = ldg16(src + i * 8 + 8), u2 = ldg16(src + i * 8 + 16), u3 = ldg16(src + i * 8 + 24);
;       float f[8];
;       unpack8(u0, f);
; #pragma unroll
;       for (int e = 0; e < 8; ++e) s += f[e] * f[e];
;       unpack8(u1, f);
; #pragma unroll
;       for (int e = 0; e < 8; ++e) s += f[e] * f[e];
;       unpack8(u2, f);
; #pragma unroll
;       for (int e = 0; e < 8; ++e) s += f[e] * f[e];
;       unpack8(u3, f);
; #pragma unroll
;       for (int e = 0; e < 8; ++e) s += f[e] * f[e];
;     }
;     rs[tid] = rsqrtf(s / (float)KK + 1e-6f);
;   }
;   const u16* Bt = which == 0 ? (const u16*)(p.ws + O_WUQ + layer * SZ_WUQ) + (size_t)nt * 128 * 256
;                              : (const u16*)(p.ws + O_WUKV + layer * SZ_WUKV) + (size_t)nt * 128 * 128;
;   const float* Cs = (const float*)lds;
;   const float2* tab = (const float2*)(p.ws + O_TAB);
;   gemm_tile(Z + (size_t)m0 * ZW + cbase, ZW, Bt, KK, KK, lds, [&](int half) {
	v_lshlrev_b32_e32 v132, 16, v48
	v_and_b32_e32 v48, 0xffff0000, v48
	v_fmac_f32_e32 v0, v132, v132
	v_lshlrev_b32_e32 v133, 16, v49
	v_fmac_f32_e32 v0, v48, v48
	v_and_b32_e32 v49, 0xffff0000, v49
	v_fmac_f32_e32 v0, v133, v133
	v_lshlrev_b32_e32 v134, 16, v50
	v_fmac_f32_e32 v0, v49, v49
	v_and_b32_e32 v50, 0xffff0000, v50
	v_fmac_f32_e32 v0, v134, v134
	v_lshlrev_b32_e32 v135, 16, v51
	v_fmac_f32_e32 v0, v50, v50
	v_and_b32_e32 v51, 0xffff0000, v51
	v_fmac_f32_e32 v0, v135, v135
	v_fmac_f32_e32 v0, v51, v51
	v_lshlrev_b32_e32 v48, 16, v44
	v_and_b32_e32 v44, 0xffff0000, v44
	v_fmac_f32_e32 v0, v48, v48
	v_lshlrev_b32_e32 v49, 16, v45
	v_fmac_f32_e32 v0, v44, v44
	v_and_b32_e32 v45, 0xffff0000, v45
	v_fmac_f32_e32 v0, v49, v49
	v_lshlrev_b32_e32 v50, 16, v46
	v_fmac_f32_e32 v0, v45, v45
	v_and_b32_e32 v46, 0xffff0000, v46
	v_fmac_f32_e32 v0, v50, v50
	v_lshlrev_b32_e32 v51, 16, v47
	v_fmac_f32_e32 v0, v46, v46
	v_and_b32_e32 v47, 0xffff0000, v47
	v_fmac_f32_e32 v0, v51, v51
	v_fmac_f32_e32 v0, v47, v47
	v_lshlrev_b32_e32 v44, 16, v40
	v_and_b32_e32 v40, 0xffff0000, v40
	v_fmac_f32_e32 v0, v44, v44
	v_lshlrev_b32_e32 v45, 16, v41
	v_fmac_f32_e32 v0, v40, v40
	v_fmac_f32_e32 v0, v45, v45
	v_lshlrev_b32_e32 v45, 16, v42
	v_and_b32_e32 v44, 0xffff0000, v41
	v_pk_mul_f32 v[40:41], v[44:45], v[44:45]
	s_nop 0
	v_add_f32_e32 v0, v40, v0
	v_add_f32_e32 v0, v41, v0
	v_lshlrev_b32_e32 v41, 16, v43
	v_and_b32_e32 v40, 0xffff0000, v42
	v_pk_mul_f32 v[40:41], v[40:41], v[40:41]
	v_and_b32_e32 v42, 0xffff0000, v39
	v_add_f32_e32 v0, v40, v0
	v_add_f32_e32 v0, v41, v0
	v_lshlrev_b32_e32 v40, 16, v36
	v_and_b32_e32 v41, 0xffff0000, v43
	v_pk_mul_f32 v[40:41], v[40:41], v[40:41]
	s_nop 0
	v_add_f32_e32 v0, v41, v0
	v_add_f32_e32 v0, v40, v0
	v_lshlrev_b32_e32 v41, 16, v37
	v_and_b32_e32 v40, 0xffff0000, v36
	v_pk_mul_f32 v[40:41], v[40:41], v[40:41]
	s_nop 0
	v_add_f32_e32 v0, v40, v0
	v_add_f32_e32 v0, v41, v0
	v_lshlrev_b32_e32 v41, 16, v38
	v_and_b32_e32 v40, 0xffff0000, v37
	v_pk_mul_f32 v[36:37], v[40:41], v[40:41]
	s_nop 0
	v_add_f32_e32 v0, v36, v0
	v_add_f32_e32 v0, v37, v0
	v_lshlrev_b32_e32 v37, 16, v39
	v_and_b32_e32 v36, 0xffff0000, v38
	v_pk_mul_f32 v[36:37], v[36:37], v[36:37]
	s_nop 0
	v_add_f32_e32 v0, v36, v0
	v_add_f32_e32 v0, v37, v0
	v_fmac_f32_e32 v0, v42, v42
	s_waitcnt vmcnt(0)
	v_lshlrev_b32_e32 v132, 16, v64
	v_and_b32_e32 v64, 0xffff0000, v64
	v_fmac_f32_e32 v0, v132, v132
	v_lshlrev_b32_e32 v133, 16, v65
	v_fmac_f32_e32 v0, v64, v64
	v_and_b32_e32 v65, 0xffff0000, v65
	v_fmac_f32_e32 v0, v133, v133
	v_lshlrev_b32_e32 v134, 16, v66
	v_fmac_f32_e32 v0, v65, v65
	v_and_b32_e32 v66, 0xffff0000, v66
	v_fmac_f32_e32 v0, v134, v134
	v_lshlrev_b32_e32 v135, 16, v67
	v_fmac_f32_e32 v0, v66, v66
	v_and_b32_e32 v67, 0xffff0000, v67
	v_fmac_f32_e32 v0, v135, v135
	v_fmac_f32_e32 v0, v67, v67
	v_lshlrev_b32_e32 v64, 16, v60
	v_and_b32_e32 v60, 0xffff0000, v60
	v_fmac_f32_e32 v0, v64, v64
	v_lshlrev_b32_e32 v65, 16, v61
	v_fmac_f32_e32 v0, v60, v60
	v_and_b32_e32 v61, 0xffff0000, v61
	v_fmac_f32_e32 v0, v65, v65
	v_lshlrev_b32_e32 v66, 16, v62
	v_fmac_f32_e32 v0, v61, v61
	v_and_b32_e32 v62, 0xffff0000, v62
	v_fmac_f32_e32 v0, v66, v66
	v_lshlrev_b32_e32 v67, 16, v63
	v_fmac_f32_e32 v0, v62, v62
	v_and_b32_e32 v63, 0xffff0000, v63
	v_fmac_f32_e32 v0, v67, v67
	v_fmac_f32_e32 v0, v63, v63
	v_lshlrev_b32_e32 v60, 16, v56
	v_and_b32_e32 v56, 0xffff0000, v56
	v_fmac_f32_e32 v0, v60, v60
	v_lshlrev_b32_e32 v61, 16, v57
	v_fmac_f32_e32 v0, v56, v56
	v_fmac_f32_e32 v0, v61, v61
	v_lshlrev_b32_e32 v61, 16, v58
	v_and_b32_e32 v60, 0xffff0000, v57
	v_pk_mul_f32 v[56:57], v[60:61], v[60:61]
	s_nop 0
	v_add_f32_e32 v0, v56, v0
	v_add_f32_e32 v0, v57, v0
	v_lshlrev_b32_e32 v57, 16, v59
	v_and_b32_e32 v56, 0xffff0000, v58
	v_pk_mul_f32 v[56:57], v[56:57], v[56:57]
	v_and_b32_e32 v58, 0xffff0000, v55
	v_add_f32_e32 v0, v56, v0
	v_add_f32_e32 v0, v57, v0
	v_lshlrev_b32_e32 v56, 16, v52
	v_and_b32_e32 v57, 0xffff0000, v59
	v_pk_mul_f32 v[56:57], v[56:57], v[56:57]
	s_nop 0
	v_add_f32_e32 v0, v57, v0
	v_add_f32_e32 v0, v56, v0
	v_lshlrev_b32_e32 v57, 16, v53
	v_and_b32_e32 v56, 0xffff0000, v52
	v_pk_mul_f32 v[56:57], v[56:57], v[56:57]
	s_nop 0
	v_add_f32_e32 v0, v56, v0
	v_add_f32_e32 v0, v57, v0
	v_lshlrev_b32_e32 v57, 16, v54
	v_and_b32_e32 v56, 0xffff0000, v53
	v_pk_mul_f32 v[52:53], v[56:57], v[56:57]
	s_nop 0
	v_add_f32_e32 v0, v52, v0
	v_add_f32_e32 v0, v53, v0
	v_lshlrev_b32_e32 v53, 16, v55
	v_and_b32_e32 v52, 0xffff0000, v54
	v_pk_mul_f32 v[52:53], v[52:53], v[52:53]
	s_nop 0
	v_add_f32_e32 v0, v52, v0
	v_add_f32_e32 v0, v53, v0
	v_fmac_f32_e32 v0, v58, v58
	v_fmamk_f32 v0, v0, 0x3c000000, v249
	v_mul_f32_e32 v2, 0x4b800000, v0
	v_cmp_gt_f32_e32 vcc, s58, v0
	s_add_i32 s0, s39, 0xfffff010
	s_lshr_b32 s2, s0, 2
	v_cndmask_b32_e32 v0, v0, v2, vcc
	v_rsq_f32_e32 v0, v0
	s_and_b32 s17, s39, 3
	s_lshl_b32 s16, s2, 8
	s_lshl_b32 s0, s17, 15
	s_add_u32 s0, s42, s0
	s_addc_u32 s1, s43, 0
	s_mul_i32 s2, s2, 0x160000
	v_mul_f32_e32 v2, 0x45800000, v0
	v_lshlrev_b32_e32 v159, 2, v158
	s_add_u32 s2, s50, s2
	v_cndmask_b32_e32 v0, v0, v2, vcc
	v_add_u32_e32 v2, s19, v159
	s_addc_u32 s3, s51, 0
	v_mov_b32_e32 v160, v248
	ds_write_b32 v2, v0
	v_mov_b64_e32 v[2:3], s[2:3]
	v_ashrrev_i32_e32 v50, 3, v160
	v_lshlrev_b32_e32 v0, 4, v160
	v_ashrrev_i32_e32 v51, 31, v50
	v_mad_i64_i32 v[2:3], s[2:3], v50, s87, v[2:3]
	v_and_b32_e32 v0, 0x70, v0
	v_lshl_add_u64 v[138:139], v[2:3], 0, v[0:1]
	v_lshlrev_b64 v[2:3], 8, v[50:51]
	v_lshl_add_u64 v[2:3], s[0:1], 0, v[2:3]
	v_lshl_add_u64 v[134:135], v[2:3], 0, v[0:1]
	s_movk_i32 s0, 0x4000
	v_add_co_u32_e32 v136, vcc, s0, v134
; #define GT_LOAD(k0)                                                                 \
;   {                                                                                 \
;     _Pragma("unroll") for (int i_ = 0; i_ < 8; ++i_) ra[i_] = ldg16(Ap + (size_t)(i_ * 32) * lda + (k0)); \
;     _Pragma("unroll") for (int i_ = 0; i_ < 4; ++i_) rb[i_] = ldg16(Bp + (size_t)(i_ * 32) * ldb + (k0)); \
;   }
; #define GT_STORE()                                                                  \
;   {                                                                                 \
;     _Pragma("unroll") for (int i_ = 0; i_ < 8; ++i_) *(u32x4*)(Aw + i_ * 32 * GS) = ra[i_]; \
;     _Pragma("unroll") for (int i_ = 0; i_ < 4; ++i_) *(u32x4*)(Bw + i_ * 32 * GS) = rb[i_]; \
;   }
; template <typename Epi>
; DI void gemm_tile(const u16* __restrict__ A, int lda, const u16* __restrict__ Bt, int ldb, int K, char* lds, Epi epi) {
;     ...
;   const int lrow = tid >> 3, lcol = (tid & 7) * 8;
;   const u16* Ap = A + (size_t)lrow * lda + lcol;
;   const u16* Bp = Bt + (size_t)lrow * ldb + lcol;
;   u16* Aw = As + lrow * GS + lcol;
;   u16* Bw = Bs + lrow * GS + lcol;
;   u32x4 ra[8], rb[4];
;     ...
;   const int nk = K >> 6;
;   GT_LOAD(0);
;   for (int kt = 0; kt + 1 < nk; ++kt) {
;     __syncthreads();
;     GT_STORE();
;     __syncthreads();
;     GT_LOAD((kt + 1) << 6);
;     GT_COMPUTE();
;   }
;   __syncthreads();
;   GT_STORE();
;   __syncthreads();
;   GT_COMPUTE();
	s_movk_i32 s0, 0x2000
	s_nop 0
	v_addc_co_u32_e32 v137, vcc, 0, v135, vcc
	v_add_co_u32_e32 v140, vcc, s0, v134
	s_mov_b32 s0, 0x135000
	s_nop 0
	v_addc_co_u32_e32 v141, vcc, 0, v135, vcc
	v_add_co_u32_e32 v142, vcc, s0, v138
	s_mov_b32 s0, 0x109000
	s_nop 0
	v_addc_co_u32_e32 v143, vcc, 0, v139, vcc
	v_add_co_u32_e32 v144, vcc, s0, v138
	s_mov_b32 s0, 0xdd000
	s_nop 0
	v_addc_co_u32_e32 v145, vcc, 0, v139, vcc
	v_add_co_u32_e32 v146, vcc, s0, v138
	s_mov_b32 s0, 0xb1000
	s_nop 0
	v_addc_co_u32_e32 v147, vcc, 0, v139, vcc
	v_add_co_u32_e32 v148, vcc, s0, v138
	s_mov_b32 s0, 0x85000
	s_nop 0
	v_addc_co_u32_e32 v149, vcc, 0, v139, vcc
	v_add_co_u32_e32 v150, vcc, s0, v138
	s_mov_b32 s0, 0x59000
	s_nop 0
	v_addc_co_u32_e32 v151, vcc, 0, v139, vcc
	v_add_co_u32_e32 v152, vcc, s0, v138
	s_mov_b32 s0, 0x2d000
	s_nop 0
	v_addc_co_u32_e32 v153, vcc, 0, v139, vcc
	v_add_co_u32_e32 v154, vcc, s0, v138
	s_movk_i32 s2, 0x1000
	s_nop 0
	v_addc_co_u32_e32 v155, vcc, 0, v139, vcc
	v_add_co_u32_e32 v18, vcc, s2, v138
	global_load_dwordx4 v[2:5], v[136:137], off
	global_load_dwordx4 v[6:9], v[140:141], off
	global_load_dwordx4 v[10:13], v[134:135], off
	v_addc_co_u32_e32 v19, vcc, 0, v139, vcc
	global_load_dwordx4 v[14:17], v[154:155], off offset:1056
	s_nop 0
	global_load_dwordx4 v[18:21], v[18:19], off offset:1056
	s_nop 0
	global_load_dwordx4 v[22:25], v[150:151], off offset:1056
	global_load_dwordx4 v[26:29], v[152:153], off offset:1056
	global_load_dwordx4 v[30:33], v[146:147], off offset:1056
	global_load_dwordx4 v[34:37], v[148:149], off offset:1056
	global_load_dwordx4 v[38:41], v[142:143], off offset:1056
	global_load_dwordx4 v[42:45], v[144:145], off offset:1056
	s_movk_i32 s0, 0x6000
	v_add_co_u32_e32 v156, vcc, s0, v134
	v_bfe_u32 v161, v160, 5, 1
	s_nop 0
	v_addc_co_u32_e32 v157, vcc, 0, v135, vcc
	global_load_dwordx4 v[46:49], v[156:157], off
	v_mul_lo_u32 v50, v50, s60
	v_add3_u32 v163, s88, v50, v0
	v_and_b32_e32 v0, 0xfffff9f, v160
	v_lshl_add_u32 v86, v161, 4, s88
	v_mad_u64_u32 v[130:131], s[0:1], v0, s60, v[86:87]
	s_waitcnt lgkmcnt(0)
	s_barrier
	v_and_b32_e32 v0, 0x5f, v160
	v_or_b32_e32 v87, 0x60, v160
	v_mad_u64_u32 v[132:133], s[0:1], v87, s60, v[86:87]
	s_mov_b64 s[0:1], 0x1420
	s_nop 0
	v_lshl_add_u64 v[138:139], v[138:139], 0, s[0:1]
	s_lshl_b32 s8, s17, 8
	v_readlane_b32 s9, v250, 57
	s_movk_i32 s0, 0xfff
	s_add_u32 s8, s9, s8
	v_readlane_b32 s9, v250, 58
	s_mov_b32 s14, 0
	v_cmp_lt_i32_e64 s[0:1], s0, v158
	s_waitcnt vmcnt(7)
	ds_write_b128 v163, v[18:21]
	ds_write_b128 v163, v[14:17] offset:4608
	s_waitcnt vmcnt(5)
	ds_write_b128 v163, v[26:29] offset:9216
	ds_write_b128 v163, v[22:25] offset:13824
	s_waitcnt vmcnt(3)
	ds_write_b128 v163, v[34:37] offset:18432
	ds_write_b128 v163, v[30:33] offset:23040
	s_waitcnt vmcnt(1)
	ds_write_b128 v163, v[42:45] offset:27648
	ds_write_b128 v163, v[38:41] offset:32256
	ds_write_b128 v163, v[10:13] offset:36864
	ds_write_b128 v163, v[6:9] offset:41472
	ds_write_b128 v163, v[2:5] offset:46080
	s_waitcnt vmcnt(0)
	ds_write_b128 v163, v[46:49] offset:50688
	s_waitcnt lgkmcnt(0)
	s_barrier
	ds_read_b128 v[18:21], v130
	v_mul_u32_u24_e32 v2, 0x48, v0
	v_lshl_add_u32 v131, v2, 1, v86
	ds_read_b128 v[98:101], v131 offset:36864
	ds_read_b128 v[114:117], v131 offset:41472
	s_waitcnt lgkmcnt(1)
	v_mfma_f32_32x32x16_bf16 v[2:17], v[18:21], v[98:101], 0
	ds_read_b128 v[50:53], v130 offset:4608
	ds_read_b128 v[82:85], v130 offset:9216
	ds_read_b128 v[118:121], v132
	ds_read_b128 v[166:169], v130 offset:32
	ds_read_b128 v[170:173], v131 offset:36896
	ds_read_b128 v[174:177], v131 offset:41504
	v_lshlrev_b32_e32 v0, 2, v0
	s_movk_i32 s47, 0x1000
	s_waitcnt lgkmcnt(6)
	v_mfma_f32_32x32x16_bf16 v[18:33], v[18:21], v[114:117], 0
	v_cmp_gt_i32_e64 s[2:3], s2, v158
	s_addc_u32 s9, s9, 0
	s_mov_b64 s[10:11], -1
	s_waitcnt lgkmcnt(1)
	v_mfma_f32_32x32x16_bf16 v[2:17], v[166:169], v[170:173], v[2:17]
	s_waitcnt lgkmcnt(0)
	v_mfma_f32_32x32x16_bf16 v[18:33], v[166:169], v[174:177], v[18:33]
	ds_read_b128 v[166:169], v130 offset:4640
	v_mfma_f32_32x32x16_bf16 v[34:49], v[50:53], v[98:101], 0
	v_mfma_f32_32x32x16_bf16 v[50:65], v[50:53], v[114:117], 0
	s_waitcnt lgkmcnt(0)
	v_mfma_f32_32x32x16_bf16 v[34:49], v[166:169], v[170:173], v[34:49]
	v_mfma_f32_32x32x16_bf16 v[50:65], v[166:169], v[174:177], v[50:65]
	ds_read_b128 v[166:169], v130 offset:9248
	v_mfma_f32_32x32x16_bf16 v[66:81], v[82:85], v[98:101], 0
	v_mfma_f32_32x32x16_bf16 v[82:97], v[82:85], v[114:117], 0
	s_waitcnt lgkmcnt(0)
	v_mfma_f32_32x32x16_bf16 v[66:81], v[166:169], v[170:173], v[66:81]
	v_mfma_f32_32x32x16_bf16 v[82:97], v[166:169], v[174:177], v[82:97]
	ds_read_b128 v[166:169], v132 offset:32
	v_mfma_f32_32x32x16_bf16 v[98:113], v[118:121], v[98:101], 0
	v_mfma_f32_32x32x16_bf16 v[114:129], v[118:121], v[114:117], 0
	s_waitcnt lgkmcnt(0)
	v_mfma_f32_32x32x16_bf16 v[98:113], v[166:169], v[170:173], v[98:113]
	v_mfma_f32_32x32x16_bf16 v[114:129], v[166:169], v[174:177], v[114:129]
	ds_read_b128 v[166:169], v130 offset:64
	ds_read_b128 v[170:173], v131 offset:36928
	ds_read_b128 v[174:177], v131 offset:41536
	s_waitcnt lgkmcnt(1)
	v_mfma_f32_32x32x16_bf16 v[2:17], v[166:169], v[170:173], v[2:17]
	s_waitcnt lgkmcnt(0)
	v_mfma_f32_32x32x16_bf16 v[18:33], v[166:169], v[174:177], v[18:33]
	ds_read_b128 v[166:169], v130 offset:4672
	s_waitcnt lgkmcnt(0)
	v_mfma_f32_32x32x16_bf16 v[34:49], v[166:169], v[170:173], v[34:49]
	v_mfma_f32_32x32x16_bf16 v[50:65], v[166:169], v[174:177], v[50:65]
	ds_read_b128 v[166:169], v130 offset:9280
	s_waitcnt lgkmcnt(0)
; #define GT_LOAD(k0)                                                                 \
;   {                                                                                 \
;     _Pragma("unroll") for (int i_ = 0; i_ < 8; ++i_) ra[i_] = ldg16(Ap + (size_t)(i_ * 32) * lda + (k0)); \
;     _Pragma("unroll") for (int i_ = 0; i_ < 4; ++i_) rb[i_] = ldg16(Bp + (size_t)(i_ * 32) * ldb + (k0)); \
;   }
; #define GT_STORE()                                                                  \
;   {                                                                                 \
;     _Pragma("unroll") for (int i_ = 0; i_ < 8; ++i_) *(u32x4*)(Aw + i_ * 32 * GS) = ra[i_]; \
;     _Pragma("unroll") for (int i_ = 0; i_ < 4; ++i_) *(u32x4*)(Bw + i_ * 32 * GS) = rb[i_]; \
;   }
; template <typename Epi>
; DI void gemm_tile(const u16* __restrict__ A, int lda, const u16* __restrict__ Bt, int ldb, int K, char* lds, Epi epi) {
;     ...
;   const int nk = K >> 6;
;   GT_LOAD(0);
;   for (int kt = 0; kt + 1 < nk; ++kt) {
;     __syncthreads();
;     GT_STORE();
;     __syncthreads();
;     GT_LOAD((kt + 1) << 6);
;     GT_COMPUTE();
;   }
;   __syncthreads();
;   GT_STORE();
;   __syncthreads();
;   GT_COMPUTE();
	v_mfma_f32_32x32x16_bf16 v[66:81], v[166:169], v[170:173], v[66:81]
	v_mfma_f32_32x32x16_bf16 v[82:97], v[166:169], v[174:177], v[82:97]
	ds_read_b128 v[166:169], v132 offset:64
	s_waitcnt lgkmcnt(0)
	v_mfma_f32_32x32x16_bf16 v[98:113], v[166:169], v[170:173], v[98:113]
	v_mfma_f32_32x32x16_bf16 v[114:129], v[166:169], v[174:177], v[114:129]
	ds_read_b128 v[166:169], v130 offset:96
	ds_read_b128 v[170:173], v131 offset:36960
	ds_read_b128 v[174:177], v131 offset:41568
	ds_read_b128 v[178:181], v132 offset:96
	s_waitcnt lgkmcnt(2)
	v_mfma_f32_32x32x16_bf16 v[2:17], v[166:169], v[170:173], v[2:17]
	s_waitcnt lgkmcnt(1)
	v_mfma_f32_32x32x16_bf16 v[18:33], v[166:169], v[174:177], v[18:33]
	ds_read_b128 v[166:169], v130 offset:4704
	s_waitcnt lgkmcnt(0)
	v_mfma_f32_32x32x16_bf16 v[34:49], v[166:169], v[170:173], v[34:49]
	v_mfma_f32_32x32x16_bf16 v[50:65], v[166:169], v[174:177], v[50:65]
	ds_read_b128 v[166:169], v130 offset:9312
	global_load_dwordx4 v[182:185], v[138:139], off offset:128
	global_load_dwordx4 v[186:189], v[154:155], off offset:1184
	s_nop 0
	global_load_dwordx4 v[152:155], v[152:153], off offset:1184
	s_waitcnt lgkmcnt(0)
	v_mfma_f32_32x32x16_bf16 v[66:81], v[166:169], v[170:173], v[66:81]
	v_mfma_f32_32x32x16_bf16 v[82:97], v[166:169], v[174:177], v[82:97]
	global_load_dwordx4 v[166:169], v[150:151], off offset:1184
	s_nop 0
	global_load_dwordx4 v[148:151], v[148:149], off offset:1184
	s_nop 0
	global_load_dwordx4 v[218:221], v[146:147], off offset:1184
	s_nop 0
	global_load_dwordx4 v[144:147], v[144:145], off offset:1184
	s_nop 0
	global_load_dwordx4 v[222:225], v[134:135], off offset:128
	global_load_dwordx4 v[226:229], v[142:143], off offset:1184
	s_nop 0
	global_load_dwordx4 v[138:141], v[140:141], off offset:128
	v_mfma_f32_32x32x16_bf16 v[98:113], v[178:181], v[170:173], v[98:113]
	global_load_dwordx4 v[134:137], v[136:137], off offset:128
	s_nop 0
	global_load_dwordx4 v[170:173], v[156:157], off offset:128
	s_barrier
	s_waitcnt vmcnt(11)
	ds_write_b128 v163, v[182:185]
	s_waitcnt vmcnt(10)
	ds_write_b128 v163, v[186:189] offset:4608
	s_waitcnt vmcnt(9)
	ds_write_b128 v163, v[152:155] offset:9216
	s_waitcnt vmcnt(8)
	ds_write_b128 v163, v[166:169] offset:13824
	s_waitcnt vmcnt(7)
	ds_write_b128 v163, v[148:151] offset:18432
	s_waitcnt vmcnt(6)
	ds_write_b128 v163, v[218:221] offset:23040
	s_waitcnt vmcnt(5)
	ds_write_b128 v163, v[144:147] offset:27648
	s_waitcnt vmcnt(3)
	ds_write_b128 v163, v[226:229] offset:32256
	ds_write_b128 v163, v[222:225] offset:36864
	s_waitcnt vmcnt(2)
	ds_write_b128 v163, v[138:141] offset:41472
	s_waitcnt vmcnt(1)
	ds_write_b128 v163, v[134:137] offset:46080
	s_waitcnt vmcnt(0)
	ds_write_b128 v163, v[170:173] offset:50688
	s_waitcnt lgkmcnt(0)
	s_barrier
	ds_read_b128 v[134:137], v130
	ds_read_b128 v[138:141], v131 offset:36864
	ds_read_b128 v[142:145], v131 offset:41472
	s_waitcnt lgkmcnt(1)
	v_mfma_f32_32x32x16_bf16 v[2:17], v[134:137], v[138:141], v[2:17]
	s_waitcnt lgkmcnt(0)
	v_mfma_f32_32x32x16_bf16 v[18:33], v[134:137], v[142:145], v[18:33]
	ds_read_b128 v[134:137], v130 offset:4608
	s_waitcnt lgkmcnt(0)
	v_mfma_f32_32x32x16_bf16 v[34:49], v[134:137], v[138:141], v[34:49]
	v_mfma_f32_32x32x16_bf16 v[50:65], v[134:137], v[142:145], v[50:65]
	ds_read_b128 v[134:137], v130 offset:9216
	s_waitcnt lgkmcnt(0)
	v_mfma_f32_32x32x16_bf16 v[66:81], v[134:137], v[138:141], v[66:81]
	v_mfma_f32_32x32x16_bf16 v[82:97], v[134:137], v[142:145], v[82:97]
	ds_read_b128 v[134:137], v132
	v_mfma_f32_32x32x16_bf16 v[114:129], v[178:181], v[174:177], v[114:129]
	s_waitcnt lgkmcnt(0)
	v_mfma_f32_32x32x16_bf16 v[98:113], v[134:137], v[138:141], v[98:113]
	v_mfma_f32_32x32x16_bf16 v[114:129], v[134:137], v[142:145], v[114:129]
	ds_read_b128 v[134:137], v130 offset:32
	ds_read_b128 v[138:141], v131 offset:36896
	ds_read_b128 v[142:145], v131 offset:41504
	s_waitcnt lgkmcnt(1)
	v_mfma_f32_32x32x16_bf16 v[2:17], v[134:137], v[138:141], v[2:17]
	s_waitcnt lgkmcnt(0)
	v_mfma_f32_32x32x16_bf16 v[18:33], v[134:137], v[142:145], v[18:33]
	ds_read_b128 v[134:137], v130 offset:4640
	s_waitcnt lgkmcnt(0)
	v_mfma_f32_32x32x16_bf16 v[34:49], v[134:137], v[138:141], v[34:49]
	v_mfma_f32_32x32x16_bf16 v[50:65], v[134:137], v[142:145], v[50:65]
	ds_read_b128 v[134:137], v130 offset:9248
	s_waitcnt lgkmcnt(0)
	v_mfma_f32_32x32x16_bf16 v[66:81], v[134:137], v[138:141], v[66:81]
	v_mfma_f32_32x32x16_bf16 v[82:97], v[134:137], v[142:145], v[82:97]
	ds_read_b128 v[134:137], v132 offset:32
	s_waitcnt lgkmcnt(0)
	v_mfma_f32_32x32x16_bf16 v[98:113], v[134:137], v[138:141], v[98:113]
	v_mfma_f32_32x32x16_bf16 v[114:129], v[134:137], v[142:145], v[114:129]
	ds_read_b128 v[134:137], v130 offset:64
	ds_read_b128 v[138:141], v131 offset:36928
	ds_read_b128 v[142:145], v131 offset:41536
	s_waitcnt lgkmcnt(1)
	v_mfma_f32_32x32x16_bf16 v[2:17], v[134:137], v[138:141], v[2:17]
	s_waitcnt lgkmcnt(0)
	v_mfma_f32_32x32x16_bf16 v[18:33], v[134:137], v[142:145], v[18:33]
	ds_read_b128 v[134:137], v130 offset:4672
	s_waitcnt lgkmcnt(0)
	v_mfma_f32_32x32x16_bf16 v[34:49], v[134:137], v[138:141], v[34:49]
	v_mfma_f32_32x32x16_bf16 v[50:65], v[134:137], v[142:145], v[50:65]
	ds_read_b128 v[134:137], v130 offset:9280
	s_waitcnt lgkmcnt(0)
	v_mfma_f32_32x32x16_bf16 v[66:81], v[134:137], v[138:141], v[66:81]
	v_mfma_f32_32x32x16_bf16 v[82:97], v[134:137], v[142:145], v[82:97]
	ds_read_b128 v[134:137], v132 offset:64
	s_waitcnt lgkmcnt(0)
	v_mfma_f32_32x32x16_bf16 v[98:113], v[134:137], v[138:141], v[98:113]
	v_mfma_f32_32x32x16_bf16 v[114:129], v[134:137], v[142:145], v[114:129]
	ds_read_b128 v[134:137], v130 offset:96
	ds_read_b128 v[138:141], v131 offset:36960
	ds_read_b128 v[142:145], v131 offset:41568
	v_mul_u32_u24_e32 v131, 0x210, v161
	v_lshlrev_b32_e32 v131, 2, v131
	v_add3_u32 v131, s88, v131, v0
	s_waitcnt lgkmcnt(1)
	v_mfma_f32_32x32x16_bf16 v[2:17], v[134:137], v[138:141], v[2:17]
	s_waitcnt lgkmcnt(0)
	v_mfma_f32_32x32x16_bf16 v[18:33], v[134:137], v[142:145], v[18:33]
	ds_read_b128 v[134:137], v130 offset:4704
	s_waitcnt lgkmcnt(0)
	v_mfma_f32_32x32x16_bf16 v[34:49], v[134:137], v[138:141], v[34:49]
	v_mfma_f32_32x32x16_bf16 v[50:65], v[134:137], v[142:145], v[50:65]
	ds_read_b128 v[134:137], v130 offset:9312
	v_ashrrev_i32_e32 v130, 7, v160
	s_waitcnt lgkmcnt(0)
	v_mfma_f32_32x32x16_bf16 v[66:81], v[134:137], v[138:141], v[66:81]
	v_mfma_f32_32x32x16_bf16 v[82:97], v[134:137], v[142:145], v[82:97]
	ds_read_b128 v[132:135], v132 offset:96
	s_waitcnt lgkmcnt(0)
	v_mfma_f32_32x32x16_bf16 v[98:113], v[132:135], v[138:141], v[98:113]
	v_mfma_f32_32x32x16_bf16 v[114:129], v[132:135], v[142:145], v[114:129]
	s_branch .LBB0_228

; DI void prep_mla(const Params& p, int layer, int tm, int which, int nt, char* lds) {
;     ...
;     for (int i = 0; i < KK / 8; i += 4) {
;       u32x4 u0 = ldg16(src + i * 8), u1 = ldg16(src + i * 8 + 8), u2 = ldg16(src + i * 8 + 16), u3 = ldg16(src + i * 8 + 24);
;       float f[8];
;       unpack8(u0, f);
; #pragma unroll
;       for (int e = 0; e < 8; ++e) s += f[e] * f[e];
;       unpack8(u1, f);
; #pragma unroll
;       for (int e = 0; e < 8; ++e) s += f[e] * f[e];
;       unpack8(u2, f);
; #pragma unroll
;       for (int e = 0; e < 8; ++e) s += f[e] * f[e];
;       unpack8(u3, f);
; #pragma unroll
;       for (int e = 0; e < 8; ++e) s += f[e] * f[e];
;     }
.LBB0_242:
	global_load_dwordx4 v[4:7], v[2:3], off offset:48
	global_load_dwordx4 v[8:11], v[2:3], off offset:32
	global_load_dwordx4 v[12:15], v[2:3], off offset:16
	global_load_dwordx4 v[16:19], v[2:3], off offset:0
	global_load_dwordx4 v[20:23], v[2:3], off offset:112
	global_load_dwordx4 v[24:27], v[2:3], off offset:96
	global_load_dwordx4 v[28:31], v[2:3], off offset:80
	global_load_dwordx4 v[32:35], v[2:3], off offset:64
	global_load_dwordx4 v[36:39], v[2:3], off offset:176
	global_load_dwordx4 v[40:43], v[2:3], off offset:160
	global_load_dwordx4 v[44:47], v[2:3], off offset:144
	global_load_dwordx4 v[48:51], v[2:3], off offset:128
	global_load_dwordx4 v[52:55], v[2:3], off offset:240
	global_load_dwordx4 v[56:59], v[2:3], off offset:224
	global_load_dwordx4 v[60:63], v[2:3], off offset:208
	global_load_dwordx4 v[64:67], v[2:3], off offset:192
	global_load_dwordx4 v[68:71], v[2:3], off offset:304
	global_load_dwordx4 v[72:75], v[2:3], off offset:288
	global_load_dwordx4 v[76:79], v[2:3], off offset:272
	global_load_dwordx4 v[80:83], v[2:3], off offset:256
	global_load_dwordx4 v[84:87], v[2:3], off offset:368
	global_load_dwordx4 v[88:91], v[2:3], off offset:352
	global_load_dwordx4 v[92:95], v[2:3], off offset:336
	global_load_dwordx4 v[96:99], v[2:3], off offset:320
	global_load_dwordx4 v[100:103], v[2:3], off offset:432
	global_load_dwordx4 v[104:107], v[2:3], off offset:416
	global_load_dwordx4 v[108:111], v[2:3], off offset:400
	global_load_dwordx4 v[112:115], v[2:3], off offset:384
	global_load_dwordx4 v[116:119], v[2:3], off offset:496
	global_load_dwordx4 v[120:123], v[2:3], off offset:480
	global_load_dwordx4 v[124:127], v[2:3], off offset:464
	global_load_dwordx4 v[128:131], v[2:3], off offset:448
	s_waitcnt vmcnt(28)
	v_lshlrev_b32_e32 v132, 16, v16
	v_and_b32_e32 v16, 0xffff0000, v16
	v_fmac_f32_e32 v0, v132, v132
	v_lshlrev_b32_e32 v133, 16, v17
	v_fmac_f32_e32 v0, v16, v16
	v_and_b32_e32 v17, 0xffff0000, v17
	v_fmac_f32_e32 v0, v133, v133
	v_lshlrev_b32_e32 v134, 16, v18
	v_fmac_f32_e32 v0, v17, v17
	v_and_b32_e32 v18, 0xffff0000, v18
	v_fmac_f32_e32 v0, v134, v134
	v_lshlrev_b32_e32 v135, 16, v19
	v_fmac_f32_e32 v0, v18, v18
	v_and_b32_e32 v19, 0xffff0000, v19
	v_fmac_f32_e32 v0, v135, v135
	v_fmac_f32_e32 v0, v19, v19
	v_lshlrev_b32_e32 v16, 16, v12
	v_and_b32_e32 v12, 0xffff0000, v12
	v_fmac_f32_e32 v0, v16, v16
	v_lshlrev_b32_e32 v17, 16, v13
	v_fmac_f32_e32 v0, v12, v12
	v_and_b32_e32 v13, 0xffff0000, v13
	v_fmac_f32_e32 v0, v17, v17
	v_lshlrev_b32_e32 v18, 16, v14
	v_fmac_f32_e32 v0, v13, v13
	v_and_b32_e32 v14, 0xffff0000, v14
	v_fmac_f32_e32 v0, v18, v18
	v_lshlrev_b32_e32 v19, 16, v15
	v_fmac_f32_e32 v0, v14, v14
	v_and_b32_e32 v15, 0xffff0000, v15
	v_fmac_f32_e32 v0, v19, v19
	v_fmac_f32_e32 v0, v15, v15
	v_lshlrev_b32_e32 v12, 16, v8
	v_and_b32_e32 v8, 0xffff0000, v8
	v_fmac_f32_e32 v0, v12, v12
	v_lshlrev_b32_e32 v13, 16, v9
	v_fmac_f32_e32 v0, v8, v8
	v_fmac_f32_e32 v0, v13, v13
	v_lshlrev_b32_e32 v13, 16, v10
	v_and_b32_e32 v12, 0xffff0000, v9
	v_pk_mul_f32 v[8:9], v[12:13], v[12:13]
	s_nop 0
	v_add_f32_e32 v0, v8, v0
	v_add_f32_e32 v0, v9, v0
	v_lshlrev_b32_e32 v9, 16, v11
	v_and_b32_e32 v8, 0xffff0000, v10
	v_pk_mul_f32 v[8:9], v[8:9], v[8:9]
	v_and_b32_e32 v10, 0xffff0000, v7
	v_add_f32_e32 v0, v8, v0
	v_add_f32_e32 v0, v9, v0
	v_lshlrev_b32_e32 v8, 16, v4
	v_and_b32_e32 v9, 0xffff0000, v11
	v_pk_mul_f32 v[8:9], v[8:9], v[8:9]
	s_nop 0
	v_add_f32_e32 v0, v9, v0
	v_add_f32_e32 v0, v8, v0
	v_lshlrev_b32_e32 v9, 16, v5
	v_and_b32_e32 v8, 0xffff0000, v4
	v_pk_mul_f32 v[8:9], v[8:9], v[8:9]
	s_nop 0
	v_add_f32_e32 v0, v8, v0
	v_add_f32_e32 v0, v9, v0
	v_lshlrev_b32_e32 v9, 16, v6
	v_and_b32_e32 v8, 0xffff0000, v5
	v_pk_mul_f32 v[4:5], v[8:9], v[8:9]
	s_nop 0
	v_add_f32_e32 v0, v4, v0
	v_add_f32_e32 v0, v5, v0
	v_lshlrev_b32_e32 v5, 16, v7
	v_and_b32_e32 v4, 0xffff0000, v6
	v_pk_mul_f32 v[4:5], v[4:5], v[4:5]
	s_nop 0
	v_add_f32_e32 v0, v4, v0
	v_add_f32_e32 v0, v5, v0
	v_fmac_f32_e32 v0, v10, v10
	s_waitcnt vmcnt(24)
	v_lshlrev_b32_e32 v132, 16, v32
	v_and_b32_e32 v32, 0xffff0000, v32
	v_fmac_f32_e32 v0, v132, v132
	v_lshlrev_b32_e32 v133, 16, v33
	v_fmac_f32_e32 v0, v32, v32
	v_and_b32_e32 v33, 0xffff0000, v33
	v_fmac_f32_e32 v0, v133, v133
	v_lshlrev_b32_e32 v134, 16, v34
	v_fmac_f32_e32 v0, v33, v33
	v_and_b32_e32 v34, 0xffff0000, v34
	v_fmac_f32_e32 v0, v134, v134
	v_lshlrev_b32_e32 v135, 16, v35
	v_fmac_f32_e32 v0, v34, v34
	v_and_b32_e32 v35, 0xffff0000, v35
	v_fmac_f32_e32 v0, v135, v135
	v_fmac_f32_e32 v0, v35, v35
	v_lshlrev_b32_e32 v32, 16, v28
	v_and_b32_e32 v28, 0xffff0000, v28
	v_fmac_f32_e32 v0, v32, v32
	v_lshlrev_b32_e32 v33, 16, v29
	v_fmac_f32_e32 v0, v28, v28
	v_and_b32_e32 v29, 0xffff0000, v29
	v_fmac_f32_e32 v0, v33, v33
	v_lshlrev_b32_e32 v34, 16, v30
	v_fmac_f32_e32 v0, v29, v29
	v_and_b32_e32 v30, 0xffff0000, v30
	v_fmac_f32_e32 v0, v34, v34
	v_lshlrev_b32_e32 v35, 16, v31
	v_fmac_f32_e32 v0, v30, v30
	v_and_b32_e32 v31, 0xffff0000, v31
	v_fmac_f32_e32 v0, v35, v35
	v_fmac_f32_e32 v0, v31, v31
	v_lshlrev_b32_e32 v28, 16, v24
	v_and_b32_e32 v24, 0xffff0000, v24
	v_fmac_f32_e32 v0, v28, v28
	v_lshlrev_b32_e32 v29, 16, v25
	v_fmac_f32_e32 v0, v24, v24
	v_fmac_f32_e32 v0, v29, v29
	v_lshlrev_b32_e32 v29, 16, v26
	v_and_b32_e32 v28, 0xffff0000, v25
	v_pk_mul_f32 v[24:25], v[28:29], v[28:29]
	s_nop 0
	v_add_f32_e32 v0, v24, v0
	v_add_f32_e32 v0, v25, v0
	v_lshlrev_b32_e32 v25, 16, v27
	v_and_b32_e32 v24, 0xffff0000, v26
	v_pk_mul_f32 v[24:25], v[24:25], v[24:25]
	v_and_b32_e32 v26, 0xffff0000, v23
	v_add_f32_e32 v0, v24, v0
	v_add_f32_e32 v0, v25, v0
	v_lshlrev_b32_e32 v24, 16, v20
	v_and_b32_e32 v25, 0xffff0000, v27
	v_pk_mul_f32 v[24:25], v[24:25], v[24:25]
	s_nop 0
	v_add_f32_e32 v0, v25, v0
	v_add_f32_e32 v0, v24, v0
	v_lshlrev_b32_e32 v25, 16, v21
	v_and_b32_e32 v24, 0xffff0000, v20
	v_pk_mul_f32 v[24:25], v[24:25], v[24:25]
	s_nop 0
	v_add_f32_e32 v0, v24, v0
	v_add_f32_e32 v0, v25, v0
	v_lshlrev_b32_e32 v25, 16, v22
	v_and_b32_e32 v24, 0xffff0000, v21
	v_pk_mul_f32 v[20:21], v[24:25], v[24:25]
	s_nop 0
	v_add_f32_e32 v0, v20, v0
	v_add_f32_e32 v0, v21, v0
	v_lshlrev_b32_e32 v21, 16, v23
	v_and_b32_e32 v20, 0xffff0000, v22
	v_pk_mul_f32 v[20:21], v[20:21], v[20:21]
	s_nop 0
	v_add_f32_e32 v0, v20, v0
	v_add_f32_e32 v0, v21, v0
	v_fmac_f32_e32 v0, v26, v26
	s_waitcnt vmcnt(20)
; DI void prep_mla(const Params& p, int layer, int tm, int which, int nt, char* lds) {
;     ...
;     for (int i = 0; i < KK / 8; i += 4) {
;       u32x4 u0 = ldg16(src + i * 8), u1 = ldg16(src + i * 8 + 8), u2 = ldg16(src + i * 8 + 16), u3 = ldg16(src + i * 8 + 24);
;       float f[8];
;       unpack8(u0, f);
; #pragma unroll
;       for (int e = 0; e < 8; ++e) s += f[e] * f[e];
;       unpack8(u1, f);
; #pragma unroll
;       for (int e = 0; e < 8; ++e) s += f[e] * f[e];
;       unpack8(u2, f);
; #pragma unroll
;       for (int e = 0; e < 8; ++e) s += f[e] * f[e];
;       unpack8(u3, f);
; #pragma unroll
;       for (int e = 0; e < 8; ++e) s += f[e] * f[e];
;     }
	v_lshlrev_b32_e32 v132, 16, v48
	v_and_b32_e32 v48, 0xffff0000, v48
	v_fmac_f32_e32 v0, v132, v132
	v_lshlrev_b32_e32 v133, 16, v49
	v_fmac_f32_e32 v0, v48, v48
	v_and_b32_e32 v49, 0xffff0000, v49
	v_fmac_f32_e32 v0, v133, v133
	v_lshlrev_b32_e32 v134, 16, v50
	v_fmac_f32_e32 v0, v49, v49
	v_and_b32_e32 v50, 0xffff0000, v50
	v_fmac_f32_e32 v0, v134, v134
	v_lshlrev_b32_e32 v135, 16, v51
	v_fmac_f32_e32 v0, v50, v50
	v_and_b32_e32 v51, 0xffff0000, v51
	v_fmac_f32_e32 v0, v135, v135
	v_fmac_f32_e32 v0, v51, v51
	v_lshlrev_b32_e32 v48, 16, v44
	v_and_b32_e32 v44, 0xffff0000, v44
	v_fmac_f32_e32 v0, v48, v48
	v_lshlrev_b32_e32 v49, 16, v45
	v_fmac_f32_e32 v0, v44, v44
	v_and_b32_e32 v45, 0xffff0000, v45
	v_fmac_f32_e32 v0, v49, v49
	v_lshlrev_b32_e32 v50, 16, v46
	v_fmac_f32_e32 v0, v45, v45
	v_and_b32_e32 v46, 0xffff0000, v46
	v_fmac_f32_e32 v0, v50, v50
	v_lshlrev_b32_e32 v51, 16, v47
	v_fmac_f32_e32 v0, v46, v46
	v_and_b32_e32 v47, 0xffff0000, v47
	v_fmac_f32_e32 v0, v51, v51
	v_fmac_f32_e32 v0, v47, v47
	v_lshlrev_b32_e32 v44, 16, v40
	v_and_b32_e32 v40, 0xffff0000, v40
	v_fmac_f32_e32 v0, v44, v44
	v_lshlrev_b32_e32 v45, 16, v41
	v_fmac_f32_e32 v0, v40, v40
	v_fmac_f32_e32 v0, v45, v45
	v_lshlrev_b32_e32 v45, 16, v42
	v_and_b32_e32 v44, 0xffff0000, v41
	v_pk_mul_f32 v[40:41], v[44:45], v[44:45]
	s_nop 0
	v_add_f32_e32 v0, v40, v0
	v_add_f32_e32 v0, v41, v0
	v_lshlrev_b32_e32 v41, 16, v43
	v_and_b32_e32 v40, 0xffff0000, v42
	v_pk_mul_f32 v[40:41], v[40:41], v[40:41]
	v_and_b32_e32 v42, 0xffff0000, v39
	v_add_f32_e32 v0, v40, v0
	v_add_f32_e32 v0, v41, v0
	v_lshlrev_b32_e32 v40, 16, v36
	v_and_b32_e32 v41, 0xffff0000, v43
	v_pk_mul_f32 v[40:41], v[40:41], v[40:41]
	s_nop 0
	v_add_f32_e32 v0, v41, v0
	v_add_f32_e32 v0, v40, v0
	v_lshlrev_b32_e32 v41, 16, v37
	v_and_b32_e32 v40, 0xffff0000, v36
	v_pk_mul_f32 v[40:41], v[40:41], v[40:41]
	s_nop 0
	v_add_f32_e32 v0, v40, v0
	v_add_f32_e32 v0, v41, v0
	v_lshlrev_b32_e32 v41, 16, v38
	v_and_b32_e32 v40, 0xffff0000, v37
	v_pk_mul_f32 v[36:37], v[40:41], v[40:41]
	s_nop 0
	v_add_f32_e32 v0, v36, v0
	v_add_f32_e32 v0, v37, v0
	v_lshlrev_b32_e32 v37, 16, v39
	v_and_b32_e32 v36, 0xffff0000, v38
	v_pk_mul_f32 v[36:37], v[36:37], v[36:37]
	s_nop 0
	v_add_f32_e32 v0, v36, v0
	v_add_f32_e32 v0, v37, v0
	v_fmac_f32_e32 v0, v42, v42
	s_waitcnt vmcnt(16)
	v_lshlrev_b32_e32 v132, 16, v64
	v_and_b32_e32 v64, 0xffff0000, v64
	v_fmac_f32_e32 v0, v132, v132
	v_lshlrev_b32_e32 v133, 16, v65
	v_fmac_f32_e32 v0, v64, v64
	v_and_b32_e32 v65, 0xffff0000, v65
	v_fmac_f32_e32 v0, v133, v133
	v_lshlrev_b32_e32 v134, 16, v66
	v_fmac_f32_e32 v0, v65, v65
	v_and_b32_e32 v66, 0xffff0000, v66
	v_fmac_f32_e32 v0, v134, v134
	v_lshlrev_b32_e32 v135, 16, v67
	v_fmac_f32_e32 v0, v66, v66
	v_and_b32_e32 v67, 0xffff0000, v67
	v_fmac_f32_e32 v0, v135, v135
	v_fmac_f32_e32 v0, v67, v67
	v_lshlrev_b32_e32 v64, 16, v60
	v_and_b32_e32 v60, 0xffff0000, v60
	v_fmac_f32_e32 v0, v64, v64
	v_lshlrev_b32_e32 v65, 16, v61
	v_fmac_f32_e32 v0, v60, v60
	v_and_b32_e32 v61, 0xffff0000, v61
	v_fmac_f32_e32 v0, v65, v65
	v_lshlrev_b32_e32 v66, 16, v62
	v_fmac_f32_e32 v0, v61, v61
	v_and_b32_e32 v62, 0xffff0000, v62
	v_fmac_f32_e32 v0, v66, v66
	v_lshlrev_b32_e32 v67, 16, v63
	v_fmac_f32_e32 v0, v62, v62
	v_and_b32_e32 v63, 0xffff0000, v63
	v_fmac_f32_e32 v0, v67, v67
	v_fmac_f32_e32 v0, v63, v63
	v_lshlrev_b32_e32 v60, 16, v56
	v_and_b32_e32 v56, 0xffff0000, v56
	v_fmac_f32_e32 v0, v60, v60
	v_lshlrev_b32_e32 v61, 16, v57
	v_fmac_f32_e32 v0, v56, v56
	v_fmac_f32_e32 v0, v61, v61
	v_lshlrev_b32_e32 v61, 16, v58
	v_and_b32_e32 v60, 0xffff0000, v57
	v_pk_mul_f32 v[56:57], v[60:61], v[60:61]
	s_nop 0
	v_add_f32_e32 v0, v56, v0
	v_add_f32_e32 v0, v57, v0
	v_lshlrev_b32_e32 v57, 16, v59
	v_and_b32_e32 v56, 0xffff0000, v58
	v_pk_mul_f32 v[56:57], v[56:57], v[56:57]
	v_and_b32_e32 v58, 0xffff0000, v55
	v_add_f32_e32 v0, v56, v0
	v_add_f32_e32 v0, v57, v0
	v_lshlrev_b32_e32 v56, 16, v52
	v_and_b32_e32 v57, 0xffff0000, v59
	v_pk_mul_f32 v[56:57], v[56:57], v[56:57]
	s_nop 0
	v_add_f32_e32 v0, v57, v0
	v_add_f32_e32 v0, v56, v0
	v_lshlrev_b32_e32 v57, 16, v53
	v_and_b32_e32 v56, 0xffff0000, v52
	v_pk_mul_f32 v[56:57], v[56:57], v[56:57]
	s_nop 0
	v_add_f32_e32 v0, v56, v0
	v_add_f32_e32 v0, v57, v0
	v_lshlrev_b32_e32 v57, 16, v54
	v_and_b32_e32 v56, 0xffff0000, v53
	v_pk_mul_f32 v[52:53], v[56:57], v[56:57]
	s_nop 0
	v_add_f32_e32 v0, v52, v0
	v_add_f32_e32 v0, v53, v0
	v_lshlrev_b32_e32 v53, 16, v55
	v_and_b32_e32 v52, 0xffff0000, v54
	v_pk_mul_f32 v[52:53], v[52:53], v[52:53]
	s_nop 0
	v_add_f32_e32 v0, v52, v0
	v_add_f32_e32 v0, v53, v0
	v_fmac_f32_e32 v0, v58, v58
	s_waitcnt vmcnt(12)
; DI void prep_mla(const Params& p, int layer, int tm, int which, int nt, char* lds) {
;     ...
;     for (int i = 0; i < KK / 8; i += 4) {
;       u32x4 u0 = ldg16(src + i * 8), u1 = ldg16(src + i * 8 + 8), u2 = ldg16(src + i * 8 + 16), u3 = ldg16(src + i * 8 + 24);
;       float f[8];
;       unpack8(u0, f);
; #pragma unroll
;       for (int e = 0; e < 8; ++e) s += f[e] * f[e];
;       unpack8(u1, f);
; #pragma unroll
;       for (int e = 0; e < 8; ++e) s += f[e] * f[e];
;       unpack8(u2, f);
; #pragma unroll
;       for (int e = 0; e < 8; ++e) s += f[e] * f[e];
;       unpack8(u3, f);
; #pragma unroll
;       for (int e = 0; e < 8; ++e) s += f[e] * f[e];
;     }
	v_lshlrev_b32_e32 v132, 16, v80
	v_and_b32_e32 v80, 0xffff0000, v80
	v_fmac_f32_e32 v0, v132, v132
	v_lshlrev_b32_e32 v133, 16, v81
	v_fmac_f32_e32 v0, v80, v80
	v_and_b32_e32 v81, 0xffff0000, v81
	v_fmac_f32_e32 v0, v133, v133
	v_lshlrev_b32_e32 v134, 16, v82
	v_fmac_f32_e32 v0, v81, v81
	v_and_b32_e32 v82, 0xffff0000, v82
	v_fmac_f32_e32 v0, v134, v134
	v_lshlrev_b32_e32 v135, 16, v83
	v_fmac_f32_e32 v0, v82, v82
	v_and_b32_e32 v83, 0xffff0000, v83
	v_fmac_f32_e32 v0, v135, v135
	v_fmac_f32_e32 v0, v83, v83
	v_lshlrev_b32_e32 v80, 16, v76
	v_and_b32_e32 v76, 0xffff0000, v76
	v_fmac_f32_e32 v0, v80, v80
	v_lshlrev_b32_e32 v81, 16, v77
	v_fmac_f32_e32 v0, v76, v76
	v_and_b32_e32 v77, 0xffff0000, v77
	v_fmac_f32_e32 v0, v81, v81
	v_lshlrev_b32_e32 v82, 16, v78
	v_fmac_f32_e32 v0, v77, v77
	v_and_b32_e32 v78, 0xffff0000, v78
	v_fmac_f32_e32 v0, v82, v82
	v_lshlrev_b32_e32 v83, 16, v79
	v_fmac_f32_e32 v0, v78, v78
	v_and_b32_e32 v79, 0xffff0000, v79
	v_fmac_f32_e32 v0, v83, v83
	v_fmac_f32_e32 v0, v79, v79
	v_lshlrev_b32_e32 v76, 16, v72
	v_and_b32_e32 v72, 0xffff0000, v72
	v_fmac_f32_e32 v0, v76, v76
	v_lshlrev_b32_e32 v77, 16, v73
	v_fmac_f32_e32 v0, v72, v72
	v_fmac_f32_e32 v0, v77, v77
	v_lshlrev_b32_e32 v77, 16, v74
	v_and_b32_e32 v76, 0xffff0000, v73
	v_pk_mul_f32 v[72:73], v[76:77], v[76:77]
	s_nop 0
	v_add_f32_e32 v0, v72, v0
	v_add_f32_e32 v0, v73, v0
	v_lshlrev_b32_e32 v73, 16, v75
	v_and_b32_e32 v72, 0xffff0000, v74
	v_pk_mul_f32 v[72:73], v[72:73], v[72:73]
	v_and_b32_e32 v74, 0xffff0000, v71
	v_add_f32_e32 v0, v72, v0
	v_add_f32_e32 v0, v73, v0
	v_lshlrev_b32_e32 v72, 16, v68
	v_and_b32_e32 v73, 0xffff0000, v75
	v_pk_mul_f32 v[72:73], v[72:73], v[72:73]
	s_nop 0
	v_add_f32_e32 v0, v73, v0
	v_add_f32_e32 v0, v72, v0
	v_lshlrev_b32_e32 v73, 16, v69
	v_and_b32_e32 v72, 0xffff0000, v68
	v_pk_mul_f32 v[72:73], v[72:73], v[72:73]
	s_nop 0
	v_add_f32_e32 v0, v72, v0
	v_add_f32_e32 v0, v73, v0
	v_lshlrev_b32_e32 v73, 16, v70
	v_and_b32_e32 v72, 0xffff0000, v69
	v_pk_mul_f32 v[68:69], v[72:73], v[72:73]
	s_nop 0
	v_add_f32_e32 v0, v68, v0
	v_add_f32_e32 v0, v69, v0
	v_lshlrev_b32_e32 v69, 16, v71
	v_and_b32_e32 v68, 0xffff0000, v70
	v_pk_mul_f32 v[68:69], v[68:69], v[68:69]
	s_nop 0
	v_add_f32_e32 v0, v68, v0
	v_add_f32_e32 v0, v69, v0
	v_fmac_f32_e32 v0, v74, v74
	s_waitcnt vmcnt(8)
	v_lshlrev_b32_e32 v132, 16, v96
	v_and_b32_e32 v96, 0xffff0000, v96
	v_fmac_f32_e32 v0, v132, v132
	v_lshlrev_b32_e32 v133, 16, v97
	v_fmac_f32_e32 v0, v96, v96
	v_and_b32_e32 v97, 0xffff0000, v97
	v_fmac_f32_e32 v0, v133, v133
	v_lshlrev_b32_e32 v134, 16, v98
	v_fmac_f32_e32 v0, v97, v97
	v_and_b32_e32 v98, 0xffff0000, v98
	v_fmac_f32_e32 v0, v134, v134
	v_lshlrev_b32_e32 v135, 16, v99
	v_fmac_f32_e32 v0, v98, v98
	v_and_b32_e32 v99, 0xffff0000, v99
	v_fmac_f32_e32 v0, v135, v135
	v_fmac_f32_e32 v0, v99, v99
	v_lshlrev_b32_e32 v96, 16, v92
	v_and_b32_e32 v92, 0xffff0000, v92
	v_fmac_f32_e32 v0, v96, v96
	v_lshlrev_b32_e32 v97, 16, v93
	v_fmac_f32_e32 v0, v92, v92
	v_and_b32_e32 v93, 0xffff0000, v93
	v_fmac_f32_e32 v0, v97, v97
	v_lshlrev_b32_e32 v98, 16, v94
	v_fmac_f32_e32 v0, v93, v93
	v_and_b32_e32 v94, 0xffff0000, v94
	v_fmac_f32_e32 v0, v98, v98
	v_lshlrev_b32_e32 v99, 16, v95
	v_fmac_f32_e32 v0, v94, v94
	v_and_b32_e32 v95, 0xffff0000, v95
	v_fmac_f32_e32 v0, v99, v99
	v_fmac_f32_e32 v0, v95, v95
	v_lshlrev_b32_e32 v92, 16, v88
	v_and_b32_e32 v88, 0xffff0000, v88
	v_fmac_f32_e32 v0, v92, v92
	v_lshlrev_b32_e32 v93, 16, v89
	v_fmac_f32_e32 v0, v88, v88
	v_fmac_f32_e32 v0, v93, v93
	v_lshlrev_b32_e32 v93, 16, v90
	v_and_b32_e32 v92, 0xffff0000, v89
	v_pk_mul_f32 v[88:89], v[92:93], v[92:93]
	s_nop 0
	v_add_f32_e32 v0, v88, v0
	v_add_f32_e32 v0, v89, v0
	v_lshlrev_b32_e32 v89, 16, v91
	v_and_b32_e32 v88, 0xffff0000, v90
	v_pk_mul_f32 v[88:89], v[88:89], v[88:89]
	v_and_b32_e32 v90, 0xffff0000, v87
	v_add_f32_e32 v0, v88, v0
	v_add_f32_e32 v0, v89, v0
	v_lshlrev_b32_e32 v88, 16, v84
	v_and_b32_e32 v89, 0xffff0000, v91
	v_pk_mul_f32 v[88:89], v[88:89], v[88:89]
	s_nop 0
	v_add_f32_e32 v0, v89, v0
	v_add_f32_e32 v0, v88, v0
	v_lshlrev_b32_e32 v89, 16, v85
	v_and_b32_e32 v88, 0xffff0000, v84
	v_pk_mul_f32 v[88:89], v[88:89], v[88:89]
	s_nop 0
	v_add_f32_e32 v0, v88, v0
	v_add_f32_e32 v0, v89, v0
	v_lshlrev_b32_e32 v89, 16, v86
	v_and_b32_e32 v88, 0xffff0000, v85
	v_pk_mul_f32 v[84:85], v[88:89], v[88:89]
	s_nop 0
	v_add_f32_e32 v0, v84, v0
	v_add_f32_e32 v0, v85, v0
	v_lshlrev_b32_e32 v85, 16, v87
	v_and_b32_e32 v84, 0xffff0000, v86
	v_pk_mul_f32 v[84:85], v[84:85], v[84:85]
	s_nop 0
	v_add_f32_e32 v0, v84, v0
	v_add_f32_e32 v0, v85, v0
	v_fmac_f32_e32 v0, v90, v90
	s_waitcnt vmcnt(4)
; DI void prep_mla(const Params& p, int layer, int tm, int which, int nt, char* lds) {
;     ...
;     for (int i = 0; i < KK / 8; i += 4) {
;       u32x4 u0 = ldg16(src + i * 8), u1 = ldg16(src + i * 8 + 8), u2 = ldg16(src + i * 8 + 16), u3 = ldg16(src + i * 8 + 24);
;       float f[8];
;       unpack8(u0, f);
; #pragma unroll
;       for (int e = 0; e < 8; ++e) s += f[e] * f[e];
;       unpack8(u1, f);
; #pragma unroll
;       for (int e = 0; e < 8; ++e) s += f[e] * f[e];
;       unpack8(u2, f);
; #pragma unroll
;       for (int e = 0; e < 8; ++e) s += f[e] * f[e];
;       unpack8(u3, f);
; #pragma unroll
;       for (int e = 0; e < 8; ++e) s += f[e] * f[e];
;     }
;     rs[tid] = rsqrtf(s / (float)KK + 1e-6f);
;   }
;   const u16* Bt = which == 0 ? (const u16*)(p.ws + O_WUQ + layer * SZ_WUQ) + (size_t)nt * 128 * 256
;                              : (const u16*)(p.ws + O_WUKV + layer * SZ_WUKV) + (size_t)nt * 128 * 128;
;   const float* Cs = (const float*)lds;
;   const float2* tab = (const float2*)(p.ws + O_TAB);
;   gemm_tile(Z + (size_t)m0 * ZW + cbase, ZW, Bt, KK, KK, lds, [&](int half) {
	v_lshlrev_b32_e32 v132, 16, v112
	v_and_b32_e32 v112, 0xffff0000, v112
	v_fmac_f32_e32 v0, v132, v132
	v_lshlrev_b32_e32 v133, 16, v113
	v_fmac_f32_e32 v0, v112, v112
	v_and_b32_e32 v113, 0xffff0000, v113
	v_fmac_f32_e32 v0, v133, v133
	v_lshlrev_b32_e32 v134, 16, v114
	v_fmac_f32_e32 v0, v113, v113
	v_and_b32_e32 v114, 0xffff0000, v114
	v_fmac_f32_e32 v0, v134, v134
	v_lshlrev_b32_e32 v135, 16, v115
	v_fmac_f32_e32 v0, v114, v114
	v_and_b32_e32 v115, 0xffff0000, v115
	v_fmac_f32_e32 v0, v135, v135
	v_fmac_f32_e32 v0, v115, v115
	v_lshlrev_b32_e32 v112, 16, v108
	v_and_b32_e32 v108, 0xffff0000, v108
	v_fmac_f32_e32 v0, v112, v112
	v_lshlrev_b32_e32 v113, 16, v109
	v_fmac_f32_e32 v0, v108, v108
	v_and_b32_e32 v109, 0xffff0000, v109
	v_fmac_f32_e32 v0, v113, v113
	v_lshlrev_b32_e32 v114, 16, v110
	v_fmac_f32_e32 v0, v109, v109
	v_and_b32_e32 v110, 0xffff0000, v110
	v_fmac_f32_e32 v0, v114, v114
	v_lshlrev_b32_e32 v115, 16, v111
	v_fmac_f32_e32 v0, v110, v110
	v_and_b32_e32 v111, 0xffff0000, v111
	v_fmac_f32_e32 v0, v115, v115
	v_fmac_f32_e32 v0, v111, v111
	v_lshlrev_b32_e32 v108, 16, v104
	v_and_b32_e32 v104, 0xffff0000, v104
	v_fmac_f32_e32 v0, v108, v108
	v_lshlrev_b32_e32 v109, 16, v105
	v_fmac_f32_e32 v0, v104, v104
	v_fmac_f32_e32 v0, v109, v109
	v_lshlrev_b32_e32 v109, 16, v106
	v_and_b32_e32 v108, 0xffff0000, v105
	v_pk_mul_f32 v[104:105], v[108:109], v[108:109]
	s_nop 0
	v_add_f32_e32 v0, v104, v0
	v_add_f32_e32 v0, v105, v0
	v_lshlrev_b32_e32 v105, 16, v107
	v_and_b32_e32 v104, 0xffff0000, v106
	v_pk_mul_f32 v[104:105], v[104:105], v[104:105]
	v_and_b32_e32 v106, 0xffff0000, v103
	v_add_f32_e32 v0, v104, v0
	v_add_f32_e32 v0, v105, v0
	v_lshlrev_b32_e32 v104, 16, v100
	v_and_b32_e32 v105, 0xffff0000, v107
	v_pk_mul_f32 v[104:105], v[104:105], v[104:105]
	s_nop 0
	v_add_f32_e32 v0, v105, v0
	v_add_f32_e32 v0, v104, v0
	v_lshlrev_b32_e32 v105, 16, v101
	v_and_b32_e32 v104, 0xffff0000, v100
	v_pk_mul_f32 v[104:105], v[104:105], v[104:105]
	s_nop 0
	v_add_f32_e32 v0, v104, v0
	v_add_f32_e32 v0, v105, v0
	v_lshlrev_b32_e32 v105, 16, v102
	v_and_b32_e32 v104, 0xffff0000, v101
	v_pk_mul_f32 v[100:101], v[104:105], v[104:105]
	s_nop 0
	v_add_f32_e32 v0, v100, v0
	v_add_f32_e32 v0, v101, v0
	v_lshlrev_b32_e32 v101, 16, v103
	v_and_b32_e32 v100, 0xffff0000, v102
	v_pk_mul_f32 v[100:101], v[100:101], v[100:101]
	s_nop 0
	v_add_f32_e32 v0, v100, v0
	v_add_f32_e32 v0, v101, v0
	v_fmac_f32_e32 v0, v106, v106
	s_waitcnt vmcnt(0)
	v_lshlrev_b32_e32 v132, 16, v128
	v_and_b32_e32 v128, 0xffff0000, v128
	v_fmac_f32_e32 v0, v132, v132
	v_lshlrev_b32_e32 v133, 16, v129
	v_fmac_f32_e32 v0, v128, v128
	v_and_b32_e32 v129, 0xffff0000, v129
	v_fmac_f32_e32 v0, v133, v133
	v_lshlrev_b32_e32 v134, 16, v130
	v_fmac_f32_e32 v0, v129, v129
	v_and_b32_e32 v130, 0xffff0000, v130
	v_fmac_f32_e32 v0, v134, v134
	v_lshlrev_b32_e32 v135, 16, v131
	v_fmac_f32_e32 v0, v130, v130
	v_and_b32_e32 v131, 0xffff0000, v131
	v_fmac_f32_e32 v0, v135, v135
	v_fmac_f32_e32 v0, v131, v131
	v_lshlrev_b32_e32 v128, 16, v124
	v_and_b32_e32 v124, 0xffff0000, v124
	v_fmac_f32_e32 v0, v128, v128
	v_lshlrev_b32_e32 v129, 16, v125
	v_fmac_f32_e32 v0, v124, v124
	v_and_b32_e32 v125, 0xffff0000, v125
	v_fmac_f32_e32 v0, v129, v129
	v_lshlrev_b32_e32 v130, 16, v126
	v_fmac_f32_e32 v0, v125, v125
	v_and_b32_e32 v126, 0xffff0000, v126
	v_fmac_f32_e32 v0, v130, v130
	v_lshlrev_b32_e32 v131, 16, v127
	v_fmac_f32_e32 v0, v126, v126
	v_and_b32_e32 v127, 0xffff0000, v127
	v_fmac_f32_e32 v0, v131, v131
	v_fmac_f32_e32 v0, v127, v127
	v_lshlrev_b32_e32 v124, 16, v120
	v_and_b32_e32 v120, 0xffff0000, v120
	v_fmac_f32_e32 v0, v124, v124
	v_lshlrev_b32_e32 v125, 16, v121
	v_fmac_f32_e32 v0, v120, v120
	v_fmac_f32_e32 v0, v125, v125
	v_lshlrev_b32_e32 v125, 16, v122
	v_and_b32_e32 v124, 0xffff0000, v121
	v_pk_mul_f32 v[120:121], v[124:125], v[124:125]
	s_nop 0
	v_add_f32_e32 v0, v120, v0
	v_add_f32_e32 v0, v121, v0
	v_lshlrev_b32_e32 v121, 16, v123
	v_and_b32_e32 v120, 0xffff0000, v122
	v_pk_mul_f32 v[120:121], v[120:121], v[120:121]
	v_and_b32_e32 v122, 0xffff0000, v119
	v_add_f32_e32 v0, v120, v0
	v_add_f32_e32 v0, v121, v0
	v_lshlrev_b32_e32 v120, 16, v116
	v_and_b32_e32 v121, 0xffff0000, v123
	v_pk_mul_f32 v[120:121], v[120:121], v[120:121]
	s_nop 0
	v_add_f32_e32 v0, v121, v0
	v_add_f32_e32 v0, v120, v0
	v_lshlrev_b32_e32 v121, 16, v117
	v_and_b32_e32 v120, 0xffff0000, v116
	v_pk_mul_f32 v[120:121], v[120:121], v[120:121]
	s_nop 0
	v_add_f32_e32 v0, v120, v0
	v_add_f32_e32 v0, v121, v0
	v_lshlrev_b32_e32 v121, 16, v118
	v_and_b32_e32 v120, 0xffff0000, v117
	v_pk_mul_f32 v[116:117], v[120:121], v[120:121]
	s_nop 0
	v_add_f32_e32 v0, v116, v0
	v_add_f32_e32 v0, v117, v0
	v_lshlrev_b32_e32 v117, 16, v119
	v_and_b32_e32 v116, 0xffff0000, v118
	v_pk_mul_f32 v[116:117], v[116:117], v[116:117]
	s_nop 0
	v_add_f32_e32 v0, v116, v0
	v_add_f32_e32 v0, v117, v0
	v_fmac_f32_e32 v0, v122, v122
	v_fmamk_f32 v0, v0, 0x3b800000, v249
	v_mul_f32_e32 v2, 0x4b800000, v0
	v_cmp_gt_f32_e32 vcc, s58, v0
	s_mul_i32 s2, s0, 3
	s_sub_i32 s1, s1, s2
	v_cndmask_b32_e32 v0, v0, v2, vcc
	v_rsq_f32_e32 v0, v0
	s_and_b32 s2, s1, 0xffff
	s_lshl_b32 s1, s1, 16
	s_add_u32 s8, s44, s1
	s_addc_u32 s9, s45, 0
	s_mul_i32 s0, s0, 0x160000
	v_mul_f32_e32 v2, 0x45800000, v0
	v_lshlrev_b32_e32 v159, 2, v158
	s_add_u32 s0, s50, s0
	v_cndmask_b32_e32 v0, v0, v2, vcc
	v_add_u32_e32 v2, s19, v159
	s_addc_u32 s1, s51, 0
	v_mov_b32_e32 v160, v248
	ds_write_b32 v2, v0
	v_mov_b64_e32 v[2:3], s[0:1]
	v_ashrrev_i32_e32 v50, 3, v160
	v_lshlrev_b32_e32 v0, 4, v160
	v_ashrrev_i32_e32 v51, 31, v50
	v_mad_i64_i32 v[2:3], s[0:1], v50, s87, v[2:3]
; #define GT_LOAD(k0)                                                                 \
;   {                                                                                 \
;     _Pragma("unroll") for (int i_ = 0; i_ < 8; ++i_) ra[i_] = ldg16(Ap + (size_t)(i_ * 32) * lda + (k0)); \
;     _Pragma("unroll") for (int i_ = 0; i_ < 4; ++i_) rb[i_] = ldg16(Bp + (size_t)(i_ * 32) * ldb + (k0)); \
;   }
; #define GT_STORE()                                                                  \
;   {                                                                                 \
;     _Pragma("unroll") for (int i_ = 0; i_ < 8; ++i_) *(u32x4*)(Aw + i_ * 32 * GS) = ra[i_]; \
;     _Pragma("unroll") for (int i_ = 0; i_ < 4; ++i_) *(u32x4*)(Bw + i_ * 32 * GS) = rb[i_]; \
;   }
; template <typename Epi>
; DI void gemm_tile(const u16* __restrict__ A, int lda, const u16* __restrict__ Bt, int ldb, int K, char* lds, Epi epi) {
;     ...
;   const int lrow = tid >> 3, lcol = (tid & 7) * 8;
;   const u16* Ap = A + (size_t)lrow * lda + lcol;
;   const u16* Bp = Bt + (size_t)lrow * ldb + lcol;
;   u16* Aw = As + lrow * GS + lcol;
;   u16* Bw = Bs + lrow * GS + lcol;
;   u32x4 ra[8], rb[4];
;     ...
;   const int nk = K >> 6;
;   GT_LOAD(0);
;   for (int kt = 0; kt + 1 < nk; ++kt) {
;     __syncthreads();
;     GT_STORE();
;     __syncthreads();
;     GT_LOAD((kt + 1) << 6);
;     GT_COMPUTE();
;   }
;   __syncthreads();
;   GT_STORE();
;   __syncthreads();
;   GT_COMPUTE();
	v_and_b32_e32 v0, 0x70, v0
	v_lshl_add_u64 v[156:157], v[2:3], 0, v[0:1]
	v_lshlrev_b64 v[2:3], 9, v[50:51]
	v_lshl_add_u64 v[2:3], s[8:9], 0, v[2:3]
	v_lshl_add_u64 v[132:133], v[2:3], 0, v[0:1]
	s_mov_b32 s0, 0x8000
	v_add_co_u32_e32 v134, vcc, s0, v132
	s_movk_i32 s0, 0x4000
	s_nop 0
	v_addc_co_u32_e32 v135, vcc, 0, v133, vcc
	v_add_co_u32_e32 v136, vcc, s0, v132
	s_mov_b32 s0, 0x135000
	s_nop 0
	v_addc_co_u32_e32 v137, vcc, 0, v133, vcc
	v_add_co_u32_e32 v140, vcc, s0, v156
	s_mov_b32 s0, 0x109000
	s_nop 0
	v_addc_co_u32_e32 v141, vcc, 0, v157, vcc
	v_add_co_u32_e32 v142, vcc, s0, v156
	s_mov_b32 s0, 0xdd000
	s_nop 0
	v_addc_co_u32_e32 v143, vcc, 0, v157, vcc
	v_add_co_u32_e32 v144, vcc, s0, v156
	s_mov_b32 s0, 0xb1000
	s_nop 0
	v_addc_co_u32_e32 v145, vcc, 0, v157, vcc
	v_add_co_u32_e32 v146, vcc, s0, v156
	s_mov_b32 s0, 0x85000
	s_nop 0
	v_addc_co_u32_e32 v147, vcc, 0, v157, vcc
	v_add_co_u32_e32 v148, vcc, s0, v156
	s_mov_b32 s0, 0x59000
	s_nop 0
	v_addc_co_u32_e32 v149, vcc, 0, v157, vcc
	v_add_co_u32_e32 v150, vcc, s0, v156
	s_mov_b32 s0, 0x2d000
	s_nop 0
	v_addc_co_u32_e32 v151, vcc, 0, v157, vcc
	v_add_co_u32_e32 v152, vcc, s0, v156
	s_movk_i32 s3, 0x1000
	s_nop 0
	v_addc_co_u32_e32 v153, vcc, 0, v157, vcc
	v_add_co_u32_e32 v18, vcc, s3, v156
	global_load_dwordx4 v[2:5], v[134:135], off
	global_load_dwordx4 v[6:9], v[136:137], off
	global_load_dwordx4 v[10:13], v[132:133], off
	v_addc_co_u32_e32 v19, vcc, 0, v157, vcc
	global_load_dwordx4 v[14:17], v[152:153], off offset:544
	s_nop 0
	global_load_dwordx4 v[18:21], v[18:19], off offset:544
	s_nop 0
	global_load_dwordx4 v[22:25], v[148:149], off offset:544
	global_load_dwordx4 v[26:29], v[150:151], off offset:544
	global_load_dwordx4 v[30:33], v[144:145], off offset:544
	global_load_dwordx4 v[34:37], v[146:147], off offset:544
	global_load_dwordx4 v[38:41], v[140:141], off offset:544
	global_load_dwordx4 v[42:45], v[142:143], off offset:544
	s_mov_b32 s0, 0xc000
	v_add_co_u32_e32 v154, vcc, s0, v132
	v_bfe_u32 v161, v160, 5, 1
	s_nop 0
	v_addc_co_u32_e32 v155, vcc, 0, v133, vcc
	global_load_dwordx4 v[46:49], v[154:155], off
	v_mul_lo_u32 v50, v50, s60
	v_add3_u32 v163, s88, v50, v0
	v_and_b32_e32 v0, 0xfffff9f, v160
	v_lshl_add_u32 v86, v161, 4, s88
	v_mad_u64_u32 v[130:131], s[0:1], v0, s60, v[86:87]
	s_waitcnt lgkmcnt(0)
	s_barrier
	v_and_b32_e32 v0, 0x5f, v160
	v_or_b32_e32 v87, 0x60, v160
	v_mad_u64_u32 v[138:139], s[0:1], v87, s60, v[86:87]
	s_mov_b64 s[0:1], 0x1220
	s_nop 0
	v_lshl_add_u64 v[156:157], v[156:157], 0, s[0:1]
	v_mov_b32_e32 v139, v248
	v_mov_b32_e32 v216, v249
	v_cmp_gt_i32_e64 s[0:1], s3, v158
	s_lshl_b32 s27, s2, 7
	s_lshl_b32 s2, s2, 8
	v_readlane_b32 s3, v251, 1
	s_add_u32 s8, s3, s2
	v_readlane_b32 s2, v251, 2
	s_waitcnt vmcnt(7)
	ds_write_b128 v163, v[18:21]
	ds_write_b128 v163, v[14:17] offset:4608
	s_waitcnt vmcnt(5)
	ds_write_b128 v163, v[26:29] offset:9216
	ds_write_b128 v163, v[22:25] offset:13824
	s_waitcnt vmcnt(3)
	ds_write_b128 v163, v[34:37] offset:18432
	ds_write_b128 v163, v[30:33] offset:23040
	s_waitcnt vmcnt(1)
	ds_write_b128 v163, v[42:45] offset:27648
	ds_write_b128 v163, v[38:41] offset:32256
	ds_write_b128 v163, v[10:13] offset:36864
	ds_write_b128 v163, v[6:9] offset:41472
	ds_write_b128 v163, v[2:5] offset:46080
	s_waitcnt vmcnt(0)
	ds_write_b128 v163, v[46:49] offset:50688
	s_waitcnt lgkmcnt(0)
	s_barrier
	ds_read_b128 v[18:21], v130
	v_mul_u32_u24_e32 v2, 0x48, v0
	v_lshl_add_u32 v131, v2, 1, v86
	ds_read_b128 v[98:101], v131 offset:36864
	ds_read_b128 v[166:169], v130 offset:32
	ds_read_b128 v[170:173], v131 offset:36896
	ds_read_b128 v[114:117], v131 offset:41472
	ds_read_b128 v[174:177], v131 offset:41504
	s_waitcnt lgkmcnt(4)
	v_mfma_f32_32x32x16_bf16 v[2:17], v[18:21], v[98:101], 0
	ds_read_b128 v[50:53], v130 offset:4608
	ds_read_b128 v[218:221], v130 offset:4640
	ds_read_b128 v[82:85], v130 offset:9216
	ds_read_b128 v[222:225], v130 offset:9248
	ds_read_b128 v[118:121], v138
	ds_read_b128 v[226:229], v138 offset:32
	v_lshlrev_b32_e32 v0, 2, v0
	s_mov_b32 s14, 0
	s_movk_i32 s47, 0x1000
	s_addc_u32 s9, s2, 0
	s_waitcnt lgkmcnt(7)
	v_mfma_f32_32x32x16_bf16 v[18:33], v[18:21], v[114:117], 0
	s_or_b32 s28, s27, 1
	s_or_b32 s29, s27, 2
	s_or_b32 s30, s27, 3
	s_mov_b64 s[10:11], -1
	s_waitcnt lgkmcnt(5)
	v_mfma_f32_32x32x16_bf16 v[34:49], v[50:53], v[98:101], 0
	v_mfma_f32_32x32x16_bf16 v[50:65], v[50:53], v[114:117], 0
	s_waitcnt lgkmcnt(3)
	v_mfma_f32_32x32x16_bf16 v[66:81], v[82:85], v[98:101], 0
	v_mfma_f32_32x32x16_bf16 v[82:97], v[82:85], v[114:117], 0
	s_waitcnt lgkmcnt(1)
	v_mfma_f32_32x32x16_bf16 v[98:113], v[118:121], v[98:101], 0
	v_mfma_f32_32x32x16_bf16 v[114:129], v[118:121], v[114:117], 0
	v_mfma_f32_32x32x16_bf16 v[2:17], v[166:169], v[170:173], v[2:17]
	v_mfma_f32_32x32x16_bf16 v[18:33], v[166:169], v[174:177], v[18:33]
	v_mfma_f32_32x32x16_bf16 v[34:49], v[218:221], v[170:173], v[34:49]
	v_mfma_f32_32x32x16_bf16 v[50:65], v[218:221], v[174:177], v[50:65]
	v_mfma_f32_32x32x16_bf16 v[66:81], v[222:225], v[170:173], v[66:81]
	v_mfma_f32_32x32x16_bf16 v[82:97], v[222:225], v[174:177], v[82:97]
	s_waitcnt lgkmcnt(0)
	v_mfma_f32_32x32x16_bf16 v[98:113], v[226:229], v[170:173], v[98:113]
	v_mfma_f32_32x32x16_bf16 v[114:129], v[226:229], v[174:177], v[114:129]
	ds_read_b128 v[166:169], v130 offset:64
	ds_read_b128 v[170:173], v131 offset:36928
	ds_read_b128 v[174:177], v130 offset:96
	ds_read_b128 v[218:221], v131 offset:36960
	ds_read_b128 v[222:225], v131 offset:41536
	ds_read_b128 v[226:229], v131 offset:41568
	s_waitcnt lgkmcnt(4)
	v_mfma_f32_32x32x16_bf16 v[2:17], v[166:169], v[170:173], v[2:17]
	s_waitcnt lgkmcnt(1)
; #define GT_LOAD(k0)                                                                 \
;   {                                                                                 \
;     _Pragma("unroll") for (int i_ = 0; i_ < 8; ++i_) ra[i_] = ldg16(Ap + (size_t)(i_ * 32) * lda + (k0)); \
;     _Pragma("unroll") for (int i_ = 0; i_ < 4; ++i_) rb[i_] = ldg16(Bp + (size_t)(i_ * 32) * ldb + (k0)); \
;   }
; #define GT_STORE()                                                                  \
;   {                                                                                 \
;     _Pragma("unroll") for (int i_ = 0; i_ < 8; ++i_) *(u32x4*)(Aw + i_ * 32 * GS) = ra[i_]; \
;     _Pragma("unroll") for (int i_ = 0; i_ < 4; ++i_) *(u32x4*)(Bw + i_ * 32 * GS) = rb[i_]; \
;   }
; template <typename Epi>
; DI void gemm_tile(const u16* __restrict__ A, int lda, const u16* __restrict__ Bt, int ldb, int K, char* lds, Epi epi) {
;     ...
;   const int nk = K >> 6;
;   GT_LOAD(0);
;   for (int kt = 0; kt + 1 < nk; ++kt) {
;     __syncthreads();
;     GT_STORE();
;     __syncthreads();
;     GT_LOAD((kt + 1) << 6);
;     GT_COMPUTE();
;   }
;   __syncthreads();
;   GT_STORE();
;   __syncthreads();
;   GT_COMPUTE();
	v_mfma_f32_32x32x16_bf16 v[18:33], v[166:169], v[222:225], v[18:33]
	ds_read_b128 v[166:169], v130 offset:4672
	ds_read_b128 v[230:233], v130 offset:4704
	s_waitcnt lgkmcnt(1)
	v_mfma_f32_32x32x16_bf16 v[34:49], v[166:169], v[170:173], v[34:49]
	v_mfma_f32_32x32x16_bf16 v[50:65], v[166:169], v[222:225], v[50:65]
	ds_read_b128 v[166:169], v130 offset:9280
	ds_read_b128 v[234:237], v130 offset:9312
	s_waitcnt lgkmcnt(1)
	v_mfma_f32_32x32x16_bf16 v[66:81], v[166:169], v[170:173], v[66:81]
	v_mfma_f32_32x32x16_bf16 v[82:97], v[166:169], v[222:225], v[82:97]
	ds_read_b128 v[166:169], v138 offset:64
	ds_read_b128 v[238:241], v138 offset:96
	s_waitcnt lgkmcnt(1)
	v_mfma_f32_32x32x16_bf16 v[98:113], v[166:169], v[170:173], v[98:113]
	v_mfma_f32_32x32x16_bf16 v[114:129], v[166:169], v[222:225], v[114:129]
	v_mfma_f32_32x32x16_bf16 v[2:17], v[174:177], v[218:221], v[2:17]
	v_mfma_f32_32x32x16_bf16 v[18:33], v[174:177], v[226:229], v[18:33]
	global_load_dwordx4 v[166:169], v[156:157], off offset:128
	global_load_dwordx4 v[170:173], v[152:153], off offset:672
	global_load_dwordx4 v[174:177], v[150:151], off offset:672
	v_mfma_f32_32x32x16_bf16 v[34:49], v[230:233], v[218:221], v[34:49]
	v_mfma_f32_32x32x16_bf16 v[50:65], v[230:233], v[226:229], v[50:65]
	v_mfma_f32_32x32x16_bf16 v[66:81], v[234:237], v[218:221], v[66:81]
	v_mfma_f32_32x32x16_bf16 v[82:97], v[234:237], v[226:229], v[82:97]
	global_load_dwordx4 v[222:225], v[148:149], off offset:672
	global_load_dwordx4 v[230:233], v[146:147], off offset:672
	global_load_dwordx4 v[234:237], v[144:145], off offset:672
	global_load_dwordx4 v[242:245], v[142:143], off offset:672
	global_load_dwordx4 v[246:249], v[132:133], off offset:128
	global_load_dwordx4 v[178:181], v[140:141], off offset:672
	global_load_dwordx4 v[182:185], v[136:137], off offset:128
	s_waitcnt lgkmcnt(0)
	v_mfma_f32_32x32x16_bf16 v[98:113], v[238:241], v[218:221], v[98:113]
	global_load_dwordx4 v[218:221], v[134:135], off offset:128
	global_load_dwordx4 v[186:189], v[154:155], off offset:128
	s_barrier
	s_waitcnt vmcnt(11)
	ds_write_b128 v163, v[166:169]
	s_waitcnt vmcnt(10)
	ds_write_b128 v163, v[170:173] offset:4608
	s_waitcnt vmcnt(9)
	ds_write_b128 v163, v[174:177] offset:9216
	s_waitcnt vmcnt(8)
	ds_write_b128 v163, v[222:225] offset:13824
	s_waitcnt vmcnt(7)
	ds_write_b128 v163, v[230:233] offset:18432
	s_waitcnt vmcnt(6)
	ds_write_b128 v163, v[234:237] offset:23040
	s_waitcnt vmcnt(5)
	ds_write_b128 v163, v[242:245] offset:27648
	s_waitcnt vmcnt(3)
	ds_write_b128 v163, v[178:181] offset:32256
	ds_write_b128 v163, v[246:249] offset:36864
	s_waitcnt vmcnt(2)
	ds_write_b128 v163, v[182:185] offset:41472
	s_waitcnt vmcnt(1)
	ds_write_b128 v163, v[218:221] offset:46080
	s_waitcnt vmcnt(0)
	ds_write_b128 v163, v[186:189] offset:50688
	s_waitcnt lgkmcnt(0)
	s_barrier
	ds_read_b128 v[166:169], v130
	ds_read_b128 v[170:173], v131 offset:36864
	ds_read_b128 v[174:177], v130 offset:32
	ds_read_b128 v[178:181], v131 offset:36896
	ds_read_b128 v[182:185], v131 offset:41472
	ds_read_b128 v[186:189], v131 offset:41504
	s_waitcnt lgkmcnt(4)
	v_mfma_f32_32x32x16_bf16 v[2:17], v[166:169], v[170:173], v[2:17]
	s_waitcnt lgkmcnt(1)
	v_mfma_f32_32x32x16_bf16 v[18:33], v[166:169], v[182:185], v[18:33]
	ds_read_b128 v[166:169], v130 offset:4608
	ds_read_b128 v[218:221], v130 offset:4640
	v_mfma_f32_32x32x16_bf16 v[114:129], v[238:241], v[226:229], v[114:129]
	s_waitcnt lgkmcnt(1)
	v_mfma_f32_32x32x16_bf16 v[34:49], v[166:169], v[170:173], v[34:49]
	v_mfma_f32_32x32x16_bf16 v[50:65], v[166:169], v[182:185], v[50:65]
	ds_read_b128 v[166:169], v130 offset:9216
	ds_read_b128 v[222:225], v130 offset:9248
	s_waitcnt lgkmcnt(1)
	v_mfma_f32_32x32x16_bf16 v[66:81], v[166:169], v[170:173], v[66:81]
	v_mfma_f32_32x32x16_bf16 v[82:97], v[166:169], v[182:185], v[82:97]
	ds_read_b128 v[166:169], v138
	ds_read_b128 v[226:229], v138 offset:32
	s_waitcnt lgkmcnt(1)
	v_mfma_f32_32x32x16_bf16 v[98:113], v[166:169], v[170:173], v[98:113]
	v_mfma_f32_32x32x16_bf16 v[114:129], v[166:169], v[182:185], v[114:129]
	v_mfma_f32_32x32x16_bf16 v[2:17], v[174:177], v[178:181], v[2:17]
	v_mfma_f32_32x32x16_bf16 v[18:33], v[174:177], v[186:189], v[18:33]
	v_mfma_f32_32x32x16_bf16 v[34:49], v[218:221], v[178:181], v[34:49]
	v_mfma_f32_32x32x16_bf16 v[50:65], v[218:221], v[186:189], v[50:65]
	v_mfma_f32_32x32x16_bf16 v[66:81], v[222:225], v[178:181], v[66:81]
	v_mfma_f32_32x32x16_bf16 v[82:97], v[222:225], v[186:189], v[82:97]
	s_waitcnt lgkmcnt(0)
	v_mfma_f32_32x32x16_bf16 v[98:113], v[226:229], v[178:181], v[98:113]
	ds_read_b128 v[166:169], v130 offset:64
	ds_read_b128 v[170:173], v131 offset:36928
	ds_read_b128 v[174:177], v130 offset:96
	ds_read_b128 v[178:181], v131 offset:36960
	v_mfma_f32_32x32x16_bf16 v[114:129], v[226:229], v[186:189], v[114:129]
	ds_read_b128 v[182:185], v131 offset:41536
	ds_read_b128 v[186:189], v131 offset:41568
	s_waitcnt lgkmcnt(4)
	v_mfma_f32_32x32x16_bf16 v[2:17], v[166:169], v[170:173], v[2:17]
	s_waitcnt lgkmcnt(1)
	v_mfma_f32_32x32x16_bf16 v[18:33], v[166:169], v[182:185], v[18:33]
	ds_read_b128 v[166:169], v130 offset:4672
	ds_read_b128 v[218:221], v130 offset:4704
	s_waitcnt lgkmcnt(1)
	v_mfma_f32_32x32x16_bf16 v[34:49], v[166:169], v[170:173], v[34:49]
	v_mfma_f32_32x32x16_bf16 v[50:65], v[166:169], v[182:185], v[50:65]
	ds_read_b128 v[166:169], v130 offset:9280
	ds_read_b128 v[222:225], v130 offset:9312
	s_waitcnt lgkmcnt(1)
	v_mfma_f32_32x32x16_bf16 v[66:81], v[166:169], v[170:173], v[66:81]
	v_mfma_f32_32x32x16_bf16 v[82:97], v[166:169], v[182:185], v[82:97]
	ds_read_b128 v[166:169], v138 offset:64
	ds_read_b128 v[226:229], v138 offset:96
	s_waitcnt lgkmcnt(1)
	v_mfma_f32_32x32x16_bf16 v[98:113], v[166:169], v[170:173], v[98:113]
	v_mfma_f32_32x32x16_bf16 v[114:129], v[166:169], v[182:185], v[114:129]
	v_mfma_f32_32x32x16_bf16 v[2:17], v[174:177], v[178:181], v[2:17]
	v_mfma_f32_32x32x16_bf16 v[18:33], v[174:177], v[186:189], v[18:33]
	global_load_dwordx4 v[166:169], v[156:157], off offset:256
	global_load_dwordx4 v[170:173], v[152:153], off offset:800
	global_load_dwordx4 v[174:177], v[150:151], off offset:800
	v_mfma_f32_32x32x16_bf16 v[34:49], v[218:221], v[178:181], v[34:49]
	v_mfma_f32_32x32x16_bf16 v[50:65], v[218:221], v[186:189], v[50:65]
	v_mfma_f32_32x32x16_bf16 v[66:81], v[222:225], v[178:181], v[66:81]
	v_mfma_f32_32x32x16_bf16 v[82:97], v[222:225], v[186:189], v[82:97]
	global_load_dwordx4 v[182:185], v[148:149], off offset:800
	global_load_dwordx4 v[218:221], v[146:147], off offset:800
	global_load_dwordx4 v[222:225], v[144:145], off offset:800
	global_load_dwordx4 v[230:233], v[142:143], off offset:800
	global_load_dwordx4 v[234:237], v[132:133], off offset:256
	global_load_dwordx4 v[238:241], v[140:141], off offset:800
	global_load_dwordx4 v[242:245], v[136:137], off offset:256
	s_waitcnt lgkmcnt(0)
	v_mfma_f32_32x32x16_bf16 v[98:113], v[226:229], v[178:181], v[98:113]
	global_load_dwordx4 v[178:181], v[134:135], off offset:256
	global_load_dwordx4 v[246:249], v[154:155], off offset:256
	s_barrier
; #define GT_LOAD(k0)                                                                 \
;   {                                                                                 \
;     _Pragma("unroll") for (int i_ = 0; i_ < 8; ++i_) ra[i_] = ldg16(Ap + (size_t)(i_ * 32) * lda + (k0)); \
;     _Pragma("unroll") for (int i_ = 0; i_ < 4; ++i_) rb[i_] = ldg16(Bp + (size_t)(i_ * 32) * ldb + (k0)); \
;   }
; #define GT_STORE()                                                                  \
;   {                                                                                 \
;     _Pragma("unroll") for (int i_ = 0; i_ < 8; ++i_) *(u32x4*)(Aw + i_ * 32 * GS) = ra[i_]; \
;     _Pragma("unroll") for (int i_ = 0; i_ < 4; ++i_) *(u32x4*)(Bw + i_ * 32 * GS) = rb[i_]; \
;   }
; template <typename Epi>
; DI void gemm_tile(const u16* __restrict__ A, int lda, const u16* __restrict__ Bt, int ldb, int K, char* lds, Epi epi) {
;     ...
;   const int nk = K >> 6;
;   GT_LOAD(0);
;   for (int kt = 0; kt + 1 < nk; ++kt) {
;     __syncthreads();
;     GT_STORE();
;     __syncthreads();
;     GT_LOAD((kt + 1) << 6);
;     GT_COMPUTE();
;   }
;   __syncthreads();
;   GT_STORE();
;   __syncthreads();
;   GT_COMPUTE();
	s_waitcnt vmcnt(11)
	ds_write_b128 v163, v[166:169]
	s_waitcnt vmcnt(10)
	ds_write_b128 v163, v[170:173] offset:4608
	s_waitcnt vmcnt(9)
	ds_write_b128 v163, v[174:177] offset:9216
	s_waitcnt vmcnt(8)
	ds_write_b128 v163, v[182:185] offset:13824
	s_waitcnt vmcnt(7)
	ds_write_b128 v163, v[218:221] offset:18432
	s_waitcnt vmcnt(6)
	ds_write_b128 v163, v[222:225] offset:23040
	s_waitcnt vmcnt(5)
	ds_write_b128 v163, v[230:233] offset:27648
	s_waitcnt vmcnt(3)
	ds_write_b128 v163, v[238:241] offset:32256
	ds_write_b128 v163, v[234:237] offset:36864
	s_waitcnt vmcnt(2)
	ds_write_b128 v163, v[242:245] offset:41472
	s_waitcnt vmcnt(1)
	ds_write_b128 v163, v[178:181] offset:46080
	s_waitcnt vmcnt(0)
	ds_write_b128 v163, v[246:249] offset:50688
	v_mfma_f32_32x32x16_bf16 v[114:129], v[226:229], v[186:189], v[114:129]
	s_waitcnt lgkmcnt(0)
	s_barrier
	ds_read_b128 v[166:169], v130
	ds_read_b128 v[170:173], v131 offset:36864
	ds_read_b128 v[174:177], v130 offset:32
	ds_read_b128 v[178:181], v131 offset:36896
	ds_read_b128 v[182:185], v131 offset:41472
	ds_read_b128 v[186:189], v131 offset:41504
	v_mov_b32_e32 v249, v216
	v_mov_b32_e32 v248, v139
	s_waitcnt lgkmcnt(4)
	v_mfma_f32_32x32x16_bf16 v[2:17], v[166:169], v[170:173], v[2:17]
	v_mov_b32_e32 v216, v164
	v_mov_b32_e32 v164, v208
	v_mov_b32_e32 v208, v190
	v_mov_b32_e32 v190, v191
	v_mov_b32_e32 v191, v192
	v_mov_b32_e32 v192, v193
	v_mov_b32_e32 v193, v194
	s_waitcnt lgkmcnt(1)
	v_mfma_f32_32x32x16_bf16 v[18:33], v[166:169], v[182:185], v[18:33]
	ds_read_b128 v[166:169], v130 offset:4608
	ds_read_b128 v[218:221], v130 offset:4640
	v_mov_b32_e32 v194, v196
	v_mov_b32_e32 v196, v198
	v_mov_b32_e32 v198, v200
	v_mov_b32_e32 v200, v202
	v_mov_b32_e32 v202, v204
	v_mov_b32_e32 v204, v206
	s_waitcnt lgkmcnt(1)
	v_mfma_f32_32x32x16_bf16 v[34:49], v[166:169], v[170:173], v[34:49]
	v_mov_b32_e32 v206, 0x19020
	v_mov_b32_e32 v240, 0x19860
	v_mov_b32_e32 v241, 0x1ad00
	v_mov_b32_e32 v242, 0x1b120
	v_mov_b32_e32 v243, 0x1b540
	v_mov_b32_e32 v244, 0x1b960
	v_mov_b32_e32 v245, 0x1ce00
	v_mfma_f32_32x32x16_bf16 v[50:65], v[166:169], v[182:185], v[50:65]
	ds_read_b128 v[166:169], v130 offset:9216
	ds_read_b128 v[222:225], v130 offset:9248
	v_mov_b32_e32 v246, 0x1d220
	v_mov_b32_e32 v247, 0x1d640
	s_waitcnt lgkmcnt(1)
	v_mfma_f32_32x32x16_bf16 v[66:81], v[166:169], v[170:173], v[66:81]
	v_mfma_f32_32x32x16_bf16 v[82:97], v[166:169], v[182:185], v[82:97]
	ds_read_b128 v[166:169], v138
	ds_read_b128 v[226:229], v138 offset:32
	s_waitcnt lgkmcnt(1)
	v_mfma_f32_32x32x16_bf16 v[98:113], v[166:169], v[170:173], v[98:113]
	v_mfma_f32_32x32x16_bf16 v[114:129], v[166:169], v[182:185], v[114:129]
	v_mfma_f32_32x32x16_bf16 v[2:17], v[174:177], v[178:181], v[2:17]
	v_mfma_f32_32x32x16_bf16 v[18:33], v[174:177], v[186:189], v[18:33]
	v_mfma_f32_32x32x16_bf16 v[34:49], v[218:221], v[178:181], v[34:49]
	v_mfma_f32_32x32x16_bf16 v[50:65], v[218:221], v[186:189], v[50:65]
	v_mfma_f32_32x32x16_bf16 v[66:81], v[222:225], v[178:181], v[66:81]
	v_mfma_f32_32x32x16_bf16 v[82:97], v[222:225], v[186:189], v[82:97]
	s_waitcnt lgkmcnt(0)
	v_mfma_f32_32x32x16_bf16 v[98:113], v[226:229], v[178:181], v[98:113]
	ds_read_b128 v[166:169], v130 offset:64
	ds_read_b128 v[170:173], v131 offset:36928
	ds_read_b128 v[174:177], v130 offset:96
	ds_read_b128 v[178:181], v131 offset:36960
	v_mfma_f32_32x32x16_bf16 v[114:129], v[226:229], v[186:189], v[114:129]
	ds_read_b128 v[182:185], v131 offset:41536
	ds_read_b128 v[186:189], v131 offset:41568
	s_waitcnt lgkmcnt(4)
	v_mfma_f32_32x32x16_bf16 v[2:17], v[166:169], v[170:173], v[2:17]
	s_waitcnt lgkmcnt(1)
	v_mfma_f32_32x32x16_bf16 v[18:33], v[166:169], v[182:185], v[18:33]
	ds_read_b128 v[166:169], v130 offset:4672
	ds_read_b128 v[218:221], v130 offset:4704
	s_waitcnt lgkmcnt(1)
	v_mfma_f32_32x32x16_bf16 v[34:49], v[166:169], v[170:173], v[34:49]
	v_mfma_f32_32x32x16_bf16 v[50:65], v[166:169], v[182:185], v[50:65]
	ds_read_b128 v[166:169], v130 offset:9280
	ds_read_b128 v[222:225], v130 offset:9312
	s_waitcnt lgkmcnt(1)
	v_mfma_f32_32x32x16_bf16 v[66:81], v[166:169], v[170:173], v[66:81]
	v_mfma_f32_32x32x16_bf16 v[82:97], v[166:169], v[182:185], v[82:97]
	ds_read_b128 v[166:169], v138 offset:64
	ds_read_b128 v[226:229], v138 offset:96
	s_waitcnt lgkmcnt(1)
	v_mfma_f32_32x32x16_bf16 v[98:113], v[166:169], v[170:173], v[98:113]
	v_mfma_f32_32x32x16_bf16 v[114:129], v[166:169], v[182:185], v[114:129]
	global_load_dwordx4 v[166:169], v[156:157], off offset:384
	global_load_dwordx4 v[170:173], v[152:153], off offset:928
	s_nop 0
	global_load_dwordx4 v[150:153], v[150:151], off offset:928
	v_mfma_f32_32x32x16_bf16 v[2:17], v[174:177], v[178:181], v[2:17]
	v_mfma_f32_32x32x16_bf16 v[18:33], v[174:177], v[186:189], v[18:33]
	v_mfma_f32_32x32x16_bf16 v[34:49], v[218:221], v[178:181], v[34:49]
	v_mfma_f32_32x32x16_bf16 v[50:65], v[218:221], v[186:189], v[50:65]
	v_mfma_f32_32x32x16_bf16 v[66:81], v[222:225], v[178:181], v[66:81]
	v_mfma_f32_32x32x16_bf16 v[82:97], v[222:225], v[186:189], v[82:97]
	global_load_dwordx4 v[174:177], v[148:149], off offset:928
	s_nop 0
	global_load_dwordx4 v[146:149], v[146:147], off offset:928
	s_nop 0
	global_load_dwordx4 v[182:185], v[144:145], off offset:928
	s_nop 0
	global_load_dwordx4 v[142:145], v[142:143], off offset:928
	s_nop 0
	global_load_dwordx4 v[218:221], v[132:133], off offset:384
	global_load_dwordx4 v[222:225], v[140:141], off offset:928
	global_load_dwordx4 v[230:233], v[136:137], off offset:384
	s_nop 0
	global_load_dwordx4 v[132:135], v[134:135], off offset:384
	s_nop 0
	global_load_dwordx4 v[154:157], v[154:155], off offset:384
	s_waitcnt lgkmcnt(0)
	s_barrier
; #define GT_LOAD(k0)                                                                 \
;   {                                                                                 \
;     _Pragma("unroll") for (int i_ = 0; i_ < 8; ++i_) ra[i_] = ldg16(Ap + (size_t)(i_ * 32) * lda + (k0)); \
;     _Pragma("unroll") for (int i_ = 0; i_ < 4; ++i_) rb[i_] = ldg16(Bp + (size_t)(i_ * 32) * ldb + (k0)); \
;   }
; #define GT_STORE()                                                                  \
;   {                                                                                 \
;     _Pragma("unroll") for (int i_ = 0; i_ < 8; ++i_) *(u32x4*)(Aw + i_ * 32 * GS) = ra[i_]; \
;     _Pragma("unroll") for (int i_ = 0; i_ < 4; ++i_) *(u32x4*)(Bw + i_ * 32 * GS) = rb[i_]; \
;   }
; template <typename Epi>
; DI void gemm_tile(const u16* __restrict__ A, int lda, const u16* __restrict__ Bt, int ldb, int K, char* lds, Epi epi) {
;     ...
;   const int nk = K >> 6;
;   GT_LOAD(0);
;   for (int kt = 0; kt + 1 < nk; ++kt) {
;     __syncthreads();
;     GT_STORE();
;     __syncthreads();
;     GT_LOAD((kt + 1) << 6);
;     GT_COMPUTE();
;   }
;   __syncthreads();
;   GT_STORE();
;   __syncthreads();
;   GT_COMPUTE();
	s_waitcnt vmcnt(11)
	ds_write_b128 v163, v[166:169]
	s_waitcnt vmcnt(10)
	ds_write_b128 v163, v[170:173] offset:4608
	s_waitcnt vmcnt(9)
	ds_write_b128 v163, v[150:153] offset:9216
	s_waitcnt vmcnt(8)
	ds_write_b128 v163, v[174:177] offset:13824
	s_waitcnt vmcnt(7)
	ds_write_b128 v163, v[146:149] offset:18432
	s_waitcnt vmcnt(6)
	ds_write_b128 v163, v[182:185] offset:23040
	s_waitcnt vmcnt(5)
	ds_write_b128 v163, v[142:145] offset:27648
	s_waitcnt vmcnt(3)
	ds_write_b128 v163, v[222:225] offset:32256
	ds_write_b128 v163, v[218:221] offset:36864
	s_waitcnt vmcnt(2)
	ds_write_b128 v163, v[230:233] offset:41472
	s_waitcnt vmcnt(1)
	ds_write_b128 v163, v[132:135] offset:46080
	s_waitcnt vmcnt(0)
	ds_write_b128 v163, v[154:157] offset:50688
	s_waitcnt lgkmcnt(0)
	s_barrier
	ds_read_b128 v[132:135], v130
	ds_read_b128 v[140:143], v131 offset:36864
	ds_read_b128 v[144:147], v130 offset:32
	ds_read_b128 v[148:151], v131 offset:36896
	ds_read_b128 v[152:155], v131 offset:41472
	ds_read_b128 v[166:169], v131 offset:41504
	s_waitcnt lgkmcnt(4)
	v_mfma_f32_32x32x16_bf16 v[2:17], v[132:135], v[140:143], v[2:17]
	v_mov_b32_e32 v184, 0x3727c5ac
	s_waitcnt lgkmcnt(1)
	v_mfma_f32_32x32x16_bf16 v[18:33], v[132:135], v[152:155], v[18:33]
	ds_read_b128 v[132:135], v130 offset:4608
	ds_read_b128 v[170:173], v130 offset:4640
	v_mfma_f32_32x32x16_bf16 v[98:113], v[226:229], v[178:181], v[98:113]
	v_mfma_f32_32x32x16_bf16 v[114:129], v[226:229], v[186:189], v[114:129]
	s_waitcnt lgkmcnt(1)
	v_mfma_f32_32x32x16_bf16 v[34:49], v[132:135], v[140:143], v[34:49]
	v_mfma_f32_32x32x16_bf16 v[50:65], v[132:135], v[152:155], v[50:65]
	ds_read_b128 v[132:135], v130 offset:9216
	ds_read_b128 v[174:177], v130 offset:9248
	s_waitcnt lgkmcnt(1)
	v_mfma_f32_32x32x16_bf16 v[66:81], v[132:135], v[140:143], v[66:81]
	v_mfma_f32_32x32x16_bf16 v[82:97], v[132:135], v[152:155], v[82:97]
	ds_read_b128 v[132:135], v138
	ds_read_b128 v[178:181], v138 offset:32
	s_waitcnt lgkmcnt(1)
	v_mfma_f32_32x32x16_bf16 v[98:113], v[132:135], v[140:143], v[98:113]
	v_mfma_f32_32x32x16_bf16 v[114:129], v[132:135], v[152:155], v[114:129]
	v_mfma_f32_32x32x16_bf16 v[2:17], v[144:147], v[148:151], v[2:17]
	v_mfma_f32_32x32x16_bf16 v[18:33], v[144:147], v[166:169], v[18:33]
	v_mfma_f32_32x32x16_bf16 v[34:49], v[170:173], v[148:151], v[34:49]
	v_mfma_f32_32x32x16_bf16 v[50:65], v[170:173], v[166:169], v[50:65]
	v_mfma_f32_32x32x16_bf16 v[66:81], v[174:177], v[148:151], v[66:81]
	v_mfma_f32_32x32x16_bf16 v[82:97], v[174:177], v[166:169], v[82:97]
	s_waitcnt lgkmcnt(0)
	v_mfma_f32_32x32x16_bf16 v[98:113], v[178:181], v[148:151], v[98:113]
	ds_read_b128 v[132:135], v130 offset:64
	ds_read_b128 v[140:143], v131 offset:36928
	ds_read_b128 v[144:147], v130 offset:96
	ds_read_b128 v[148:151], v131 offset:36960
	v_mfma_f32_32x32x16_bf16 v[114:129], v[178:181], v[166:169], v[114:129]
	ds_read_b128 v[152:155], v131 offset:41536
	ds_read_b128 v[166:169], v131 offset:41568
	s_waitcnt lgkmcnt(4)
	v_mfma_f32_32x32x16_bf16 v[2:17], v[132:135], v[140:143], v[2:17]
	s_waitcnt lgkmcnt(1)
	v_mfma_f32_32x32x16_bf16 v[18:33], v[132:135], v[152:155], v[18:33]
	ds_read_b128 v[132:135], v130 offset:4672
	ds_read_b128 v[170:173], v130 offset:4704
	s_waitcnt lgkmcnt(1)
	v_mfma_f32_32x32x16_bf16 v[34:49], v[132:135], v[140:143], v[34:49]
	v_mfma_f32_32x32x16_bf16 v[50:65], v[132:135], v[152:155], v[50:65]
	ds_read_b128 v[132:135], v130 offset:9280
	ds_read_b128 v[174:177], v130 offset:9312
	s_waitcnt lgkmcnt(1)
	v_mfma_f32_32x32x16_bf16 v[66:81], v[132:135], v[140:143], v[66:81]
	v_mfma_f32_32x32x16_bf16 v[82:97], v[132:135], v[152:155], v[82:97]
	ds_read_b128 v[130:133], v138 offset:64
	ds_read_b128 v[134:137], v138 offset:96
	s_waitcnt lgkmcnt(1)
	v_mfma_f32_32x32x16_bf16 v[98:113], v[130:133], v[140:143], v[98:113]
	v_ashrrev_i32_e32 v140, 7, v160
	v_mfma_f32_32x32x16_bf16 v[114:129], v[130:133], v[152:155], v[114:129]
	v_mul_u32_u24_e32 v130, 0x210, v161
	v_lshlrev_b32_e32 v130, 2, v130
	v_add3_u32 v141, s88, v130, v0
	v_mfma_f32_32x32x16_bf16 v[2:17], v[144:147], v[148:151], v[2:17]
	v_mfma_f32_32x32x16_bf16 v[18:33], v[144:147], v[166:169], v[18:33]
	v_mfma_f32_32x32x16_bf16 v[34:49], v[170:173], v[148:151], v[34:49]
	v_mfma_f32_32x32x16_bf16 v[50:65], v[170:173], v[166:169], v[50:65]
	v_mov_b32_e32 v171, 0x3e38aa3b
	v_mfma_f32_32x32x16_bf16 v[66:81], v[174:177], v[148:151], v[66:81]
	v_mfma_f32_32x32x16_bf16 v[82:97], v[174:177], v[166:169], v[82:97]
	s_waitcnt lgkmcnt(0)
	v_mfma_f32_32x32x16_bf16 v[98:113], v[134:137], v[148:151], v[98:113]
	v_mfma_f32_32x32x16_bf16 v[114:129], v[134:137], v[166:169], v[114:129]
	s_branch .LBB0_245

; DI void prep_dn(const Params& p, int layer, int tile, char* lds) {
;     ...
;   __syncthreads();
;   for (int e = tid; e < 3840; e += 256) cw[e] = p.dn_conv_w[(size_t)layer * 3840 + e];
;   __syncthreads();
.LBB0_275:
	s_andn2_b64 vcc, exec, s[0:1]
	s_cbranch_vccnz .LBB0_340
	s_waitcnt vmcnt(7)
	v_mov_b32_e32 v102, v248
	s_movk_i32 s0, 0xf00
	s_nop 0
	v_cmp_gt_i32_e32 vcc, s0, v102
	s_barrier
	s_and_saveexec_b64 s[0:1], vcc
	s_cbranch_execz .LBB0_284
	v_lshlrev_b32_e32 v2, 2, v102
	v_mov_b32_e32 v3, 0
	v_lshl_add_u64 v[2:3], s[6:7], 0, v[2:3]
	v_lshl_add_u32 v0, v102, 2, s88
	s_mov_b64 s[8:9], 0x1000
	global_load_dword v4, v[2:3], off
	global_load_dword v5, v[2:3], off offset:1024
	global_load_dword v6, v[2:3], off offset:2048
	global_load_dword v7, v[2:3], off offset:3072
	v_lshl_add_u64 v[2:3], v[2:3], 0, s[8:9]
	global_load_dword v8, v[2:3], off
	global_load_dword v9, v[2:3], off offset:1024
	global_load_dword v10, v[2:3], off offset:2048
	global_load_dword v11, v[2:3], off offset:3072
	v_lshl_add_u64 v[2:3], v[2:3], 0, s[8:9]
	global_load_dword v12, v[2:3], off
	global_load_dword v13, v[2:3], off offset:1024
	global_load_dword v14, v[2:3], off offset:2048
	global_load_dword v15, v[2:3], off offset:3072
	v_lshl_add_u64 v[2:3], v[2:3], 0, s[8:9]
	global_load_dword v16, v[2:3], off
	global_load_dword v17, v[2:3], off offset:1024
	global_load_dword v18, v[2:3], off offset:2048
	s_waitcnt vmcnt(14)
	ds_write_b32 v0, v4
	s_waitcnt vmcnt(13)
	ds_write_b32 v0, v5 offset:1024
	s_waitcnt vmcnt(12)
	ds_write_b32 v0, v6 offset:2048
	s_waitcnt vmcnt(11)
	ds_write_b32 v0, v7 offset:3072
	s_waitcnt vmcnt(10)
	ds_write_b32 v0, v8 offset:4096
	s_waitcnt vmcnt(9)
	ds_write_b32 v0, v9 offset:5120
	s_waitcnt vmcnt(8)
	ds_write_b32 v0, v10 offset:6144
	s_waitcnt vmcnt(7)
	ds_write_b32 v0, v11 offset:7168
	s_waitcnt vmcnt(6)
	ds_write_b32 v0, v12 offset:8192
	s_waitcnt vmcnt(5)
	ds_write_b32 v0, v13 offset:9216
	s_waitcnt vmcnt(4)
	ds_write_b32 v0, v14 offset:10240
	s_waitcnt vmcnt(3)
	ds_write_b32 v0, v15 offset:11264
	s_waitcnt vmcnt(2)
	ds_write_b32 v0, v16 offset:12288
	s_waitcnt vmcnt(1)
	ds_write_b32 v0, v17 offset:13312
	s_waitcnt vmcnt(0)
	ds_write_b32 v0, v18 offset:14336
